# phase 6 scaled-Q loader: the four Q loads of a k-step issued together (own scale temporaries, counted vmcnt) in three of the four ladders
# speedup vs baseline: 1.0361x; 1.0361x over previous
.LBB0_737:
	s_or_b64 exec, exec, s[2:3]
	v_mul_f32_e32 v64, v72, v64
	v_mul_f32_e32 v65, v73, v65
	ds_read_b128 v[68:71], v193
	ds_read_b128 v[72:75], v194
	v_mul_f32_e32 v67, v153, v242
	v_mul_f32_e32 v66, v155, v245
	v_readlane_b32 s0, v253, 7
	s_waitcnt lgkmcnt(1)
	v_mul_f32_e32 v76, v67, v68
	s_waitcnt lgkmcnt(0)
	v_mul_f32_e32 v72, v66, v72
	v_cndmask_b32_e64 v76, v76, 0, s[22:23]
	v_cndmask_b32_e64 v72, v72, 0, s[24:25]
	v_add_f32_e32 v72, v76, v72
	v_mul_f32_e32 v56, v56, v72
	v_mul_f32_e32 v72, v67, v69
	v_mul_f32_e32 v73, v66, v73
	v_readlane_b32 s1, v253, 8
	v_cndmask_b32_e64 v72, 0, v72, s[24:25]
	v_readlane_b32 s2, v252, 47
	v_cndmask_b32_e64 v73, v73, 0, s[0:1]
	v_add_f32_e32 v72, v72, v73
	v_readlane_b32 s0, v253, 9
	v_mul_f32_e32 v57, v57, v72
	v_mul_f32_e32 v72, v67, v70
	v_readlane_b32 s1, v253, 10
	v_mul_f32_e32 v73, v66, v74
	v_cvt_pk_bf16_f32 v56, v56, v57
	v_cndmask_b32_e64 v72, v72, 0, s[0:1]
	v_readlane_b32 s0, v253, 11
	v_readlane_b32 s1, v253, 12
	v_mov_b32_e32 v155, v125
	s_movk_i32 s97, 0x880
	v_cndmask_b32_e64 v73, v73, 0, s[0:1]
	v_add_f32_e32 v72, v72, v73
	v_readlane_b32 s0, v253, 13
	v_mul_f32_e32 v58, v58, v72
	v_mul_f32_e32 v72, v67, v71
	v_readlane_b32 s1, v253, 14
	v_mul_f32_e32 v73, v66, v75
	s_nop 0
	v_cndmask_b32_e64 v72, v72, 0, s[0:1]
	v_readlane_b32 s0, v253, 15
	v_readlane_b32 s1, v253, 16
	s_nop 1
	v_cndmask_b32_e64 v73, v73, 0, s[0:1]
	v_add_f32_e32 v72, v72, v73
	v_mul_f32_e32 v59, v59, v72
	v_cvt_pk_bf16_f32 v57, v58, v59
	ds_write_b64 v235, v[56:57] offset:36864
	v_pk_fma_f32 v[56:57], v[64:65], v[68:69], 0 op_sel_hi:[0,1,0]
	v_pk_fma_f32 v[58:59], v[64:65], v[70:71], 0 op_sel_hi:[0,1,0]
	v_pk_mul_f32 v[56:57], v[60:61], v[56:57]
	v_pk_mul_f32 v[58:59], v[62:63], v[58:59]
	v_cvt_pk_bf16_f32 v56, v56, v57
	v_cvt_pk_bf16_f32 v57, v58, v59
	ds_write_b64 v235, v[56:57] offset:41216
	ds_read_b128 v[56:59], v195
	ds_read_b128 v[60:63], v196
	v_readlane_b32 s0, v253, 17
	v_readlane_b32 s1, v253, 18
	s_waitcnt lgkmcnt(1)
	v_mul_f32_e32 v68, v67, v56
	v_cndmask_b32_e64 v68, v68, 0, s[0:1]
	v_readlane_b32 s0, v253, 19
	s_waitcnt lgkmcnt(0)
	v_mul_f32_e32 v69, v66, v60
	v_readlane_b32 s1, v253, 20
	s_nop 1
	v_cndmask_b32_e64 v69, v69, 0, s[0:1]
	v_add_f32_e32 v68, v68, v69
	v_readlane_b32 s0, v253, 21
	v_mul_f32_e32 v52, v52, v68
	v_mul_f32_e32 v68, v67, v57
	v_readlane_b32 s1, v253, 22
	v_mul_f32_e32 v69, v66, v61
	s_nop 0
	v_cndmask_b32_e64 v68, v68, 0, s[0:1]
	v_readlane_b32 s0, v253, 23
	v_readlane_b32 s1, v253, 24
	s_nop 1
	v_cndmask_b32_e64 v69, v69, 0, s[0:1]
	v_add_f32_e32 v68, v68, v69
	v_readlane_b32 s0, v253, 25
	v_mul_f32_e32 v53, v53, v68
	v_mul_f32_e32 v68, v67, v58
	v_readlane_b32 s1, v253, 26
	v_mul_f32_e32 v69, v66, v62
	v_cvt_pk_bf16_f32 v52, v52, v53
	v_cndmask_b32_e64 v68, v68, 0, s[0:1]
	v_readlane_b32 s0, v253, 27
	v_readlane_b32 s1, v253, 28
	s_nop 1
	v_cndmask_b32_e64 v69, v69, 0, s[0:1]
	v_add_f32_e32 v68, v68, v69
	v_readlane_b32 s0, v253, 29
	v_mul_f32_e32 v54, v54, v68
	v_mul_f32_e32 v68, v67, v59
	v_readlane_b32 s1, v253, 30
	v_mul_f32_e32 v69, v66, v63
	s_nop 0
	v_cndmask_b32_e64 v68, v68, 0, s[0:1]
	v_readlane_b32 s0, v253, 31
	v_readlane_b32 s1, v253, 32
	s_nop 1
	v_cndmask_b32_e64 v69, v69, 0, s[0:1]
	v_add_f32_e32 v68, v68, v69
	v_mul_f32_e32 v55, v55, v68
	v_cvt_pk_bf16_f32 v53, v54, v55
	ds_write_b64 v235, v[52:53] offset:36896
	v_mul_f32_e32 v52, v64, v56
	v_mul_f32_e32 v53, v65, v60
	v_cndmask_b32_e64 v52, v52, 0, s[22:23]
	v_cndmask_b32_e64 v53, v53, 0, s[24:25]
	v_add_f32_e32 v52, v52, v53
	v_readlane_b32 s0, v253, 33
	v_mul_f32_e32 v48, v48, v52
	v_mul_f32_e32 v52, v64, v57
	v_readlane_b32 s1, v253, 34
	v_mul_f32_e32 v53, v65, v61
	s_nop 0
	v_cndmask_b32_e64 v52, v52, 0, s[0:1]
	v_readlane_b32 s0, v253, 35
	v_readlane_b32 s1, v253, 36
	s_nop 1
	v_cndmask_b32_e64 v53, v53, 0, s[0:1]
	v_add_f32_e32 v52, v52, v53
	v_readlane_b32 s0, v253, 37
	v_mul_f32_e32 v49, v49, v52
	v_mul_f32_e32 v52, v64, v58
	v_readlane_b32 s1, v253, 38
	v_mul_f32_e32 v53, v65, v62
	v_cvt_pk_bf16_f32 v48, v48, v49
	v_cndmask_b32_e64 v52, v52, 0, s[0:1]
	v_readlane_b32 s0, v253, 39
	v_readlane_b32 s1, v253, 40
	s_nop 1
	v_cndmask_b32_e64 v53, v53, 0, s[0:1]
	v_add_f32_e32 v52, v52, v53
	v_readlane_b32 s0, v253, 41
	v_mul_f32_e32 v50, v50, v52
	v_mul_f32_e32 v52, v64, v59
	v_readlane_b32 s1, v253, 42
	v_mul_f32_e32 v53, v65, v63
	s_nop 0
	v_cndmask_b32_e64 v52, v52, 0, s[0:1]
	v_readlane_b32 s0, v253, 43
	v_readlane_b32 s1, v253, 44
	s_nop 1
	v_cndmask_b32_e64 v53, v53, 0, s[0:1]
	v_add_f32_e32 v52, v52, v53
	v_mul_f32_e32 v51, v51, v52
	v_cvt_pk_bf16_f32 v49, v50, v51
	ds_write_b64 v235, v[48:49] offset:41248
	ds_read_b128 v[48:51], v197
	ds_read_b128 v[52:55], v198
	v_readlane_b32 s0, v253, 45
	v_readlane_b32 s1, v253, 46
	s_waitcnt lgkmcnt(1)
	v_mul_f32_e32 v56, v67, v48
	v_cndmask_b32_e64 v56, v56, 0, s[0:1]
	v_readlane_b32 s0, v253, 47
	s_waitcnt lgkmcnt(0)
	v_mul_f32_e32 v57, v66, v52
	v_readlane_b32 s1, v253, 48
	s_nop 1
	v_cndmask_b32_e64 v57, v57, 0, s[0:1]
	v_add_f32_e32 v56, v56, v57
	v_readlane_b32 s0, v253, 49
	v_mul_f32_e32 v44, v44, v56
	v_mul_f32_e32 v56, v67, v49
	v_readlane_b32 s1, v253, 50
	v_mul_f32_e32 v57, v66, v53
	s_nop 0
	v_cndmask_b32_e64 v56, v56, 0, s[0:1]
	v_readlane_b32 s0, v253, 51
	v_readlane_b32 s1, v253, 52
	s_nop 1
	v_cndmask_b32_e64 v57, v57, 0, s[0:1]
	v_add_f32_e32 v56, v56, v57
	v_readlane_b32 s0, v253, 53
	v_mul_f32_e32 v45, v45, v56
	v_mul_f32_e32 v56, v67, v50
	v_readlane_b32 s1, v253, 54
	v_mul_f32_e32 v57, v66, v54
	v_cvt_pk_bf16_f32 v44, v44, v45
	v_cndmask_b32_e64 v56, v56, 0, s[0:1]
	v_readlane_b32 s0, v253, 55
	v_readlane_b32 s1, v253, 56
	s_nop 1
	v_cndmask_b32_e64 v57, v57, 0, s[0:1]
	v_add_f32_e32 v56, v56, v57
	v_readlane_b32 s0, v253, 57
	v_mul_f32_e32 v46, v46, v56
	v_mul_f32_e32 v56, v67, v51
	v_readlane_b32 s1, v253, 58
	v_mul_f32_e32 v57, v66, v55
	s_nop 0
	v_cndmask_b32_e64 v56, v56, 0, s[0:1]
	v_readlane_b32 s0, v253, 59
	v_readlane_b32 s1, v253, 60
	s_nop 1
	v_cndmask_b32_e64 v57, v57, 0, s[0:1]
	v_add_f32_e32 v56, v56, v57
	v_mul_f32_e32 v47, v47, v56
	v_cvt_pk_bf16_f32 v45, v46, v47
	v_readlane_b32 s0, v253, 61
	ds_write_b64 v235, v[44:45] offset:36928
	v_mul_f32_e32 v44, v64, v48
	v_readlane_b32 s1, v253, 62
	v_mul_f32_e32 v45, v65, v52
	s_nop 0
	v_cndmask_b32_e64 v44, v44, 0, s[0:1]
	v_readlane_b32 s0, v253, 63
	v_readlane_b32 s1, v254, 0
	s_nop 1
	v_cndmask_b32_e64 v45, v45, 0, s[0:1]
	v_add_f32_e32 v44, v44, v45
	v_readlane_b32 s0, v254, 1
	v_mul_f32_e32 v40, v40, v44
	v_mul_f32_e32 v44, v64, v49
	v_readlane_b32 s1, v254, 2
	v_mul_f32_e32 v45, v65, v53
	s_nop 0
	v_cndmask_b32_e64 v44, v44, 0, s[0:1]
	v_readlane_b32 s0, v254, 3
	v_readlane_b32 s1, v254, 4
	s_nop 1
	v_cndmask_b32_e64 v45, v45, 0, s[0:1]
	v_add_f32_e32 v44, v44, v45
	v_readlane_b32 s0, v254, 5
	v_mul_f32_e32 v41, v41, v44
	v_mul_f32_e32 v44, v64, v50
	v_readlane_b32 s1, v254, 6
	v_mul_f32_e32 v45, v65, v54
	v_cvt_pk_bf16_f32 v40, v40, v41
	v_cndmask_b32_e64 v44, v44, 0, s[0:1]
	v_readlane_b32 s0, v254, 7
	v_readlane_b32 s1, v254, 8
	s_nop 1
	v_cndmask_b32_e64 v45, v45, 0, s[0:1]
	v_add_f32_e32 v44, v44, v45
	v_readlane_b32 s0, v254, 9
	v_mul_f32_e32 v42, v42, v44
	v_mul_f32_e32 v44, v64, v51
	v_readlane_b32 s1, v254, 10
	v_mul_f32_e32 v45, v65, v55
	s_nop 0
	v_cndmask_b32_e64 v44, v44, 0, s[0:1]
	v_readlane_b32 s0, v254, 11
	v_readlane_b32 s1, v254, 12
	s_nop 1
	v_cndmask_b32_e64 v45, v45, 0, s[0:1]
	v_add_f32_e32 v44, v44, v45
	v_mul_f32_e32 v43, v43, v44
	v_cvt_pk_bf16_f32 v41, v42, v43
	ds_write_b64 v235, v[40:41] offset:41280
	ds_read_b128 v[40:43], v199
	ds_read_b128 v[44:47], v200
	v_readlane_b32 s0, v254, 13
	v_readlane_b32 s1, v254, 14
	s_waitcnt lgkmcnt(1)
	v_mul_f32_e32 v48, v67, v40
	v_cndmask_b32_e64 v48, v48, 0, s[0:1]
	v_readlane_b32 s0, v254, 15
	s_waitcnt lgkmcnt(0)
	v_mul_f32_e32 v49, v66, v44
	v_readlane_b32 s1, v254, 16
	s_nop 1
	v_cndmask_b32_e64 v49, v49, 0, s[0:1]
	v_add_f32_e32 v48, v48, v49
	v_readlane_b32 s0, v254, 17
	v_mul_f32_e32 v36, v36, v48
	v_mul_f32_e32 v48, v67, v41
	v_readlane_b32 s1, v254, 18
	v_mul_f32_e32 v49, v66, v45
	s_nop 0
	v_cndmask_b32_e64 v48, v48, 0, s[0:1]
	v_readlane_b32 s0, v254, 19
	v_readlane_b32 s1, v254, 20
	s_nop 1
	v_cndmask_b32_e64 v49, v49, 0, s[0:1]
	v_add_f32_e32 v48, v48, v49
	v_readlane_b32 s0, v254, 21
	v_mul_f32_e32 v37, v37, v48
	v_mul_f32_e32 v48, v67, v42
	v_readlane_b32 s1, v254, 22
	v_mul_f32_e32 v49, v66, v46
	v_cvt_pk_bf16_f32 v36, v36, v37
	v_cndmask_b32_e64 v48, v48, 0, s[0:1]
	v_readlane_b32 s0, v254, 23
	v_readlane_b32 s1, v254, 24
	s_nop 1
	v_cndmask_b32_e64 v49, v49, 0, s[0:1]
	v_add_f32_e32 v48, v48, v49
	v_readlane_b32 s0, v254, 25
	v_mul_f32_e32 v38, v38, v48
	v_mul_f32_e32 v48, v67, v43
	v_readlane_b32 s1, v254, 26
	v_mul_f32_e32 v49, v66, v47
	s_nop 0
	v_cndmask_b32_e64 v48, v48, 0, s[0:1]
	v_readlane_b32 s0, v254, 27
	v_readlane_b32 s1, v254, 28
	s_nop 1
	v_cndmask_b32_e64 v49, v49, 0, s[0:1]
	v_add_f32_e32 v48, v48, v49
	v_mul_f32_e32 v39, v39, v48
	v_cvt_pk_bf16_f32 v37, v38, v39
	v_readlane_b32 s0, v254, 29
	ds_write_b64 v235, v[36:37] offset:36960
	v_mul_f32_e32 v36, v64, v40
	v_readlane_b32 s1, v254, 30
	v_mul_f32_e32 v37, v65, v44
	s_nop 0
	v_cndmask_b32_e64 v36, v36, 0, s[0:1]
	v_readlane_b32 s0, v254, 31
	v_readlane_b32 s1, v254, 32
	s_nop 1
	v_cndmask_b32_e64 v37, v37, 0, s[0:1]
	v_add_f32_e32 v36, v36, v37
	v_readlane_b32 s0, v254, 33
	v_mul_f32_e32 v32, v32, v36
	v_mul_f32_e32 v36, v64, v41
	v_readlane_b32 s1, v254, 34
	v_mul_f32_e32 v37, v65, v45
	s_nop 0
	v_cndmask_b32_e64 v36, v36, 0, s[0:1]
	v_readlane_b32 s0, v254, 35
	v_readlane_b32 s1, v254, 36
	s_nop 1
	v_cndmask_b32_e64 v37, v37, 0, s[0:1]
	v_add_f32_e32 v36, v36, v37
	v_readlane_b32 s0, v254, 37
	v_mul_f32_e32 v33, v33, v36
	v_mul_f32_e32 v36, v64, v42
	v_readlane_b32 s1, v254, 38
	v_mul_f32_e32 v37, v65, v46
	v_cvt_pk_bf16_f32 v32, v32, v33
	v_cndmask_b32_e64 v36, v36, 0, s[0:1]
	v_readlane_b32 s0, v254, 39
	v_readlane_b32 s1, v254, 40
	s_nop 1
	v_cndmask_b32_e64 v37, v37, 0, s[0:1]
	v_add_f32_e32 v36, v36, v37
	v_readlane_b32 s0, v254, 41
	v_mul_f32_e32 v34, v34, v36
	v_mul_f32_e32 v36, v64, v43
	v_readlane_b32 s1, v254, 42
	v_mul_f32_e32 v37, v65, v47
	s_nop 0
	v_cndmask_b32_e64 v36, v36, 0, s[0:1]
	v_readlane_b32 s0, v254, 43
	v_readlane_b32 s1, v254, 44
	s_nop 1
	v_cndmask_b32_e64 v37, v37, 0, s[0:1]
	v_add_f32_e32 v36, v36, v37
	v_mul_f32_e32 v35, v35, v36
	v_cvt_pk_bf16_f32 v33, v34, v35
	ds_write_b64 v235, v[32:33] offset:41312
	ds_read_b128 v[32:35], v201
	ds_read_b128 v[36:39], v202
	v_readlane_b32 s0, v254, 45
	v_readlane_b32 s1, v254, 46
	s_waitcnt lgkmcnt(1)
	v_mul_f32_e32 v40, v67, v32
	v_cndmask_b32_e64 v40, v40, 0, s[0:1]
	v_readlane_b32 s0, v254, 47
	s_waitcnt lgkmcnt(0)
	v_mul_f32_e32 v41, v66, v36
	v_readlane_b32 s1, v254, 48
	s_nop 1
	v_cndmask_b32_e64 v41, v41, 0, s[0:1]
	v_add_f32_e32 v40, v40, v41
	v_readlane_b32 s0, v254, 49
	v_mul_f32_e32 v28, v28, v40
	v_mul_f32_e32 v40, v67, v33
	v_readlane_b32 s1, v254, 50
	v_mul_f32_e32 v41, v66, v37
	s_nop 0
	v_cndmask_b32_e64 v40, v40, 0, s[0:1]
	v_readlane_b32 s0, v254, 51
	v_readlane_b32 s1, v254, 52
	s_nop 1
	v_cndmask_b32_e64 v41, v41, 0, s[0:1]
	v_add_f32_e32 v40, v40, v41
	v_readlane_b32 s0, v254, 53
	v_mul_f32_e32 v29, v29, v40
	v_mul_f32_e32 v40, v67, v34
	v_readlane_b32 s1, v254, 54
	v_mul_f32_e32 v41, v66, v38
	v_cvt_pk_bf16_f32 v28, v28, v29
	v_cndmask_b32_e64 v40, v40, 0, s[0:1]
	v_readlane_b32 s0, v254, 55
	v_readlane_b32 s1, v254, 56
	s_nop 1
	v_cndmask_b32_e64 v41, v41, 0, s[0:1]
	v_add_f32_e32 v40, v40, v41
	v_readlane_b32 s0, v254, 57
	v_mul_f32_e32 v30, v30, v40
	v_mul_f32_e32 v40, v67, v35
	v_readlane_b32 s1, v254, 58
	v_mul_f32_e32 v41, v66, v39
	s_nop 0
	v_cndmask_b32_e64 v40, v40, 0, s[0:1]
	v_readlane_b32 s0, v254, 59
	v_readlane_b32 s1, v254, 60
	s_nop 1
	v_cndmask_b32_e64 v41, v41, 0, s[0:1]
	v_add_f32_e32 v40, v40, v41
	v_mul_f32_e32 v31, v31, v40
	v_cvt_pk_bf16_f32 v29, v30, v31
	v_readlane_b32 s0, v254, 61
	ds_write_b64 v235, v[28:29] offset:36992
	v_mul_f32_e32 v28, v64, v32
	v_readlane_b32 s1, v254, 62
	v_mul_f32_e32 v29, v65, v36
	s_nop 0
	v_cndmask_b32_e64 v28, v28, 0, s[0:1]
	v_readlane_b32 s0, v254, 63
	v_readlane_b32 s1, v255, 0
	s_nop 1
	v_cndmask_b32_e64 v29, v29, 0, s[0:1]
	v_add_f32_e32 v28, v28, v29
	v_readlane_b32 s0, v255, 1
	v_mul_f32_e32 v24, v24, v28
	v_mul_f32_e32 v28, v64, v33
	v_readlane_b32 s1, v255, 2
	v_mul_f32_e32 v29, v65, v37
	s_nop 0
	v_cndmask_b32_e64 v28, v28, 0, s[0:1]
	v_readlane_b32 s0, v255, 3
	v_readlane_b32 s1, v255, 4
	s_nop 1
	v_cndmask_b32_e64 v29, v29, 0, s[0:1]
	v_add_f32_e32 v28, v28, v29
	v_readlane_b32 s0, v255, 5
	v_mul_f32_e32 v25, v25, v28
	v_mul_f32_e32 v28, v64, v34
	v_readlane_b32 s1, v255, 6
	v_mul_f32_e32 v29, v65, v38
	v_cvt_pk_bf16_f32 v24, v24, v25
	v_cndmask_b32_e64 v28, v28, 0, s[0:1]
	v_readlane_b32 s0, v255, 7
	v_readlane_b32 s1, v255, 8
	s_nop 1
	v_cndmask_b32_e64 v29, v29, 0, s[0:1]
	v_add_f32_e32 v28, v28, v29
	v_readlane_b32 s0, v255, 9
	v_mul_f32_e32 v26, v26, v28
	v_mul_f32_e32 v28, v64, v35
	v_readlane_b32 s1, v255, 10
	v_mul_f32_e32 v29, v65, v39
	s_nop 0
	v_cndmask_b32_e64 v28, v28, 0, s[0:1]
	v_readlane_b32 s0, v255, 11
	v_readlane_b32 s1, v255, 12
	s_nop 1
	v_cndmask_b32_e64 v29, v29, 0, s[0:1]
	v_add_f32_e32 v28, v28, v29
	v_mul_f32_e32 v27, v27, v28
	v_cvt_pk_bf16_f32 v25, v26, v27
	ds_write_b64 v235, v[24:25] offset:41344
	ds_read_b128 v[24:27], v203
	ds_read_b128 v[28:31], v204
	v_readlane_b32 s0, v255, 13
	v_readlane_b32 s1, v255, 14
	s_waitcnt lgkmcnt(1)
	v_mul_f32_e32 v32, v67, v24
	v_cndmask_b32_e64 v32, v32, 0, s[0:1]
	v_readlane_b32 s0, v255, 15
	s_waitcnt lgkmcnt(0)
	v_mul_f32_e32 v33, v66, v28
	v_readlane_b32 s1, v255, 16
	s_nop 1
	v_cndmask_b32_e64 v33, v33, 0, s[0:1]
	v_add_f32_e32 v32, v32, v33
	v_readlane_b32 s0, v255, 17
	v_mul_f32_e32 v20, v20, v32
	v_mul_f32_e32 v32, v67, v25
	v_readlane_b32 s1, v255, 18
	v_mul_f32_e32 v33, v66, v29
	s_nop 0
	v_cndmask_b32_e64 v32, v32, 0, s[0:1]
	v_readlane_b32 s0, v255, 19
	v_readlane_b32 s1, v255, 20
	s_nop 1
	v_cndmask_b32_e64 v33, v33, 0, s[0:1]
	v_add_f32_e32 v32, v32, v33
	v_readlane_b32 s0, v255, 21
	v_mul_f32_e32 v21, v21, v32
	v_mul_f32_e32 v32, v67, v26
	v_readlane_b32 s1, v255, 22
	v_mul_f32_e32 v33, v66, v30
	v_cvt_pk_bf16_f32 v20, v20, v21
	v_cndmask_b32_e64 v32, v32, 0, s[0:1]
	v_readlane_b32 s0, v255, 23
	v_readlane_b32 s1, v255, 24
	s_nop 1
	v_cndmask_b32_e64 v33, v33, 0, s[0:1]
	v_add_f32_e32 v32, v32, v33
	v_readlane_b32 s0, v255, 25
	v_mul_f32_e32 v22, v22, v32
	v_mul_f32_e32 v32, v67, v27
	v_readlane_b32 s1, v255, 26
	v_mul_f32_e32 v33, v66, v31
	s_nop 0
	v_cndmask_b32_e64 v32, v32, 0, s[0:1]
	v_readlane_b32 s0, v255, 27
	v_readlane_b32 s1, v255, 28
	s_nop 1
	v_cndmask_b32_e64 v33, v33, 0, s[0:1]
	v_add_f32_e32 v32, v32, v33
	v_mul_f32_e32 v23, v23, v32
	v_cvt_pk_bf16_f32 v21, v22, v23
	v_readlane_b32 s0, v255, 29
	ds_write_b64 v235, v[20:21] offset:37024
	v_mul_f32_e32 v20, v64, v24
	v_readlane_b32 s1, v255, 30
	v_mul_f32_e32 v21, v65, v28
	s_nop 0
	v_cndmask_b32_e64 v20, v20, 0, s[0:1]
	v_readlane_b32 s0, v255, 31
	v_readlane_b32 s1, v255, 32
	s_nop 1
	v_cndmask_b32_e64 v21, v21, 0, s[0:1]
	v_add_f32_e32 v20, v20, v21
	v_readlane_b32 s0, v255, 33
	v_mul_f32_e32 v16, v16, v20
	v_mul_f32_e32 v20, v64, v25
	v_readlane_b32 s1, v255, 34
	v_mul_f32_e32 v21, v65, v29
	s_nop 0
	v_cndmask_b32_e64 v20, v20, 0, s[0:1]
	v_readlane_b32 s0, v255, 35
	v_readlane_b32 s1, v255, 36
	s_nop 1
	v_cndmask_b32_e64 v21, v21, 0, s[0:1]
	v_add_f32_e32 v20, v20, v21
	v_readlane_b32 s0, v255, 37
	v_mul_f32_e32 v17, v17, v20
	v_mul_f32_e32 v20, v64, v26
	v_readlane_b32 s1, v255, 38
	v_mul_f32_e32 v21, v65, v30
	v_cvt_pk_bf16_f32 v16, v16, v17
	v_cndmask_b32_e64 v20, v20, 0, s[0:1]
	v_readlane_b32 s0, v255, 39
	v_readlane_b32 s1, v255, 40
	s_nop 1
	v_cndmask_b32_e64 v21, v21, 0, s[0:1]
	v_add_f32_e32 v20, v20, v21
	v_readlane_b32 s0, v255, 41
	v_mul_f32_e32 v18, v18, v20
	v_mul_f32_e32 v20, v64, v27
	v_readlane_b32 s1, v255, 42
	v_mul_f32_e32 v21, v65, v31
	s_nop 0
	v_cndmask_b32_e64 v20, v20, 0, s[0:1]
	v_readlane_b32 s0, v255, 43
	v_readlane_b32 s1, v255, 44
	s_nop 1
	v_cndmask_b32_e64 v21, v21, 0, s[0:1]
	v_add_f32_e32 v20, v20, v21
	v_mul_f32_e32 v19, v19, v20
	v_cvt_pk_bf16_f32 v17, v18, v19
	ds_write_b64 v235, v[16:17] offset:41376
	ds_read_b128 v[16:19], v205
	ds_read_b128 v[20:23], v206
	v_readlane_b32 s0, v255, 45
	v_readlane_b32 s1, v255, 46
	s_waitcnt lgkmcnt(1)
	v_mul_f32_e32 v24, v67, v16
	v_cndmask_b32_e64 v24, v24, 0, s[0:1]
	v_readlane_b32 s0, v255, 47
	s_waitcnt lgkmcnt(0)
	v_mul_f32_e32 v25, v66, v20
	v_readlane_b32 s1, v255, 48
	s_nop 1
	v_cndmask_b32_e64 v25, v25, 0, s[0:1]
	v_add_f32_e32 v24, v24, v25
	v_readlane_b32 s0, v255, 49
	v_mul_f32_e32 v12, v12, v24
	v_mul_f32_e32 v24, v67, v17
	v_readlane_b32 s1, v255, 50
	v_mul_f32_e32 v25, v66, v21
	s_nop 0
	v_cndmask_b32_e64 v24, v24, 0, s[0:1]
	v_readlane_b32 s0, v255, 51
	v_readlane_b32 s1, v255, 52
	s_nop 1
	v_cndmask_b32_e64 v25, v25, 0, s[0:1]
	v_add_f32_e32 v24, v24, v25
	v_readlane_b32 s0, v255, 53
	v_mul_f32_e32 v13, v13, v24
	v_mul_f32_e32 v24, v67, v18
	v_readlane_b32 s1, v255, 54
	v_mul_f32_e32 v25, v66, v22
	v_cvt_pk_bf16_f32 v12, v12, v13
	v_cndmask_b32_e64 v24, v24, 0, s[0:1]
	v_readlane_b32 s0, v255, 55
	v_readlane_b32 s1, v255, 56
	s_nop 1
	v_cndmask_b32_e64 v25, v25, 0, s[0:1]
	v_add_f32_e32 v24, v24, v25
	v_mul_f32_e32 v14, v14, v24
	v_mul_f32_e32 v24, v67, v19
	v_mul_f32_e32 v25, v66, v23
	v_cndmask_b32_e64 v24, v24, 0, s[20:21]
	v_cndmask_b32_e64 v25, v25, 0, s[26:27]
	v_add_f32_e32 v24, v24, v25
	v_mul_f32_e32 v15, v15, v24
	v_cvt_pk_bf16_f32 v13, v14, v15
	ds_write_b64 v235, v[12:13] offset:37056
	v_mul_f32_e32 v12, v64, v16
	v_mul_f32_e32 v13, v65, v20
	v_cndmask_b32_e64 v12, v12, 0, s[28:29]
	v_cndmask_b32_e64 v13, v13, 0, s[30:31]
	v_add_f32_e32 v12, v12, v13
	v_mul_f32_e32 v8, v8, v12
	v_mul_f32_e32 v12, v64, v17
	v_mul_f32_e32 v13, v65, v21
	v_cndmask_b32_e64 v12, v12, 0, s[34:35]
	v_cndmask_b32_e64 v13, v13, 0, s[36:37]
	v_add_f32_e32 v12, v12, v13
	v_mul_f32_e32 v9, v9, v12
	v_mul_f32_e32 v12, v64, v18
	v_mul_f32_e32 v13, v65, v22
	v_cndmask_b32_e64 v12, v12, 0, s[38:39]
	v_cndmask_b32_e64 v13, v13, 0, s[40:41]
	v_add_f32_e32 v12, v12, v13
	v_mul_f32_e32 v10, v10, v12
	v_mul_f32_e32 v12, v64, v19
	v_mul_f32_e32 v13, v65, v23
	v_cndmask_b32_e64 v12, v12, 0, s[42:43]
	v_cndmask_b32_e64 v13, v13, 0, s[44:45]
	v_add_f32_e32 v12, v12, v13
	v_mul_f32_e32 v11, v11, v12
	v_cvt_pk_bf16_f32 v8, v8, v9
	v_cvt_pk_bf16_f32 v9, v10, v11
	ds_write_b64 v235, v[8:9] offset:41408
	ds_read_b128 v[8:11], v207
	ds_read_b128 v[12:15], v208
	s_mul_i32 s0, s12, 0x300
	s_add_i32 s0, s78, s0
	s_mul_hi_i32 s1, s0, 0x4200
	s_waitcnt lgkmcnt(1)
	v_mul_f32_e32 v16, v67, v8
	s_waitcnt lgkmcnt(0)
	v_mul_f32_e32 v17, v66, v12
	v_cndmask_b32_e64 v16, v16, 0, s[46:47]
	v_cndmask_b32_e64 v17, v17, 0, s[48:49]
	v_add_f32_e32 v16, v16, v17
	v_mul_f32_e32 v4, v4, v16
	v_mul_f32_e32 v16, v67, v9
	v_mul_f32_e32 v17, v66, v13
	v_cndmask_b32_e64 v16, v16, 0, s[50:51]
	v_cndmask_b32_e64 v17, v17, 0, s[52:53]
	v_add_f32_e32 v16, v16, v17
	v_mul_f32_e32 v5, v5, v16
	v_mul_f32_e32 v16, v67, v10
	v_mul_f32_e32 v17, v66, v14
	v_cndmask_b32_e64 v16, v16, 0, s[54:55]
	v_cndmask_b32_e64 v17, v17, 0, s[56:57]
	v_add_f32_e32 v16, v16, v17
	v_mul_f32_e32 v6, v6, v16
	v_mul_f32_e32 v16, v67, v11
	v_mul_f32_e32 v17, v66, v15
	v_cndmask_b32_e64 v16, v16, 0, s[58:59]
	v_cndmask_b32_e64 v17, v17, 0, s[60:61]
	v_add_f32_e32 v16, v16, v17
	v_mul_f32_e32 v7, v7, v16
	v_cvt_pk_bf16_f32 v4, v4, v5
	v_cvt_pk_bf16_f32 v5, v6, v7
	ds_write_b64 v235, v[4:5] offset:37088
	v_mul_f32_e32 v4, v64, v8
	v_mul_f32_e32 v5, v65, v12
	v_cndmask_b32_e64 v4, v4, 0, s[62:63]
	v_cndmask_b32_e64 v5, v5, 0, s[64:65]
	v_add_f32_e32 v4, v4, v5
	v_mul_f32_e32 v0, v0, v4
	v_mul_f32_e32 v4, v64, v9
	v_mul_f32_e32 v5, v65, v13
	v_cndmask_b32_e64 v4, v4, 0, s[66:67]
	v_cndmask_b32_e64 v5, v5, 0, s[68:69]
	v_add_f32_e32 v4, v4, v5
	v_mul_f32_e32 v1, v1, v4
	v_mul_f32_e32 v4, v64, v10
	v_mul_f32_e32 v5, v65, v14
	v_cndmask_b32_e64 v4, v4, 0, s[70:71]
	v_cndmask_b32_e64 v5, v5, 0, s[72:73]
	v_add_f32_e32 v4, v4, v5
	s_mulk_i32 s0, 0x4200
	v_mul_f32_e32 v2, v2, v4
	v_mul_f32_e32 v4, v64, v11
	v_mul_f32_e32 v5, v65, v15
	s_add_u32 s2, s2, s0
	v_readlane_b32 s0, v252, 48
	v_cndmask_b32_e64 v4, v4, 0, s[74:75]
	v_cndmask_b32_e64 v5, v5, 0, s[76:77]
	s_addc_u32 s3, s0, s1
	s_ashr_i32 s5, s4, 31
	v_add_f32_e32 v4, v4, v5
	s_lshl_b64 s[0:1], s[4:5], 1
	v_mul_f32_e32 v3, v3, v4
	s_add_u32 s0, s2, s0
	v_cvt_pk_bf16_f32 v0, v0, v1
	v_cvt_pk_bf16_f32 v1, v2, v3
	s_addc_u32 s1, s3, s1
	ds_write_b64 v235, v[0:1] offset:41440
	v_lshl_add_u64 v[0:1], s[0:1], 0, v[154:155]
	v_lshl_add_u64 v[2:3], v[0:1], 0, v[130:131]
	s_waitcnt lgkmcnt(0)
	s_barrier
	v_lshl_add_u64 v[4:5], v[0:1], 0, v[132:133]
	v_lshl_add_u64 v[6:7], v[0:1], 0, v[134:135]
	v_lshl_add_u64 v[0:1], v[0:1], 0, v[136:137]
	global_load_dwordx4 v[8:11], v[2:3], off
	global_load_dwordx4 v[12:15], v[4:5], off
	global_load_dwordx4 v[16:19], v[6:7], off
	global_load_dwordx4 v[20:23], v[0:1], off
	s_barrier
	s_waitcnt vmcnt(3)
	ds_write_b128 v236, v[8:11] offset:18432
	s_waitcnt vmcnt(2)
	ds_write_b128 v236, v[12:15] offset:23040
	s_waitcnt vmcnt(1)
	ds_write_b128 v236, v[16:19] offset:27648
	s_waitcnt vmcnt(0)
	ds_write_b128 v236, v[20:23] offset:32256
	s_waitcnt lgkmcnt(0)
	s_barrier
	ds_read_b128 v[8:11], v237 offset:36864
	ds_read_b128 v[12:15], v237 offset:41216
	ds_read_b128 v[16:19], v181 offset:18432
	ds_read_b128 v[20:23], v181 offset:20736
	ds_read_b128 v[24:27], v181 offset:23040
	ds_read_b128 v[28:31], v181 offset:25344
	ds_read_b128 v[32:35], v181 offset:27648
	ds_read_b128 v[36:39], v181 offset:29952
	ds_read_b128 v[40:43], v181 offset:32256
	ds_read_b128 v[44:47], v181 offset:34560
	s_waitcnt lgkmcnt(7)
	v_mfma_f32_16x16x32_bf16 v[48:51], v[16:19], v[8:11], 0
	s_mul_i32 s0, s12, 6
	s_add_i32 s0, s0, s96
	s_mulk_i32 s0, 0x42
	s_waitcnt lgkmcnt(6)
	v_mfma_f32_16x16x32_bf16 v[52:55], v[20:23], v[8:11], 0
	s_add_i32 s4, s0, s11
	s_ashr_i32 s5, s4, 31
	s_lshl_b64 s[0:1], s[4:5], 15
	s_waitcnt lgkmcnt(5)
	v_mfma_f32_16x16x32_bf16 v[56:59], v[24:27], v[8:11], 0
	s_movk_i32 s96, 0x600
	s_waitcnt lgkmcnt(4)
	v_mfma_f32_16x16x32_bf16 v[60:63], v[28:31], v[8:11], 0
	s_waitcnt lgkmcnt(3)
	v_mfma_f32_16x16x32_bf16 v[64:67], v[32:35], v[8:11], 0
	s_waitcnt lgkmcnt(2)
	v_mfma_f32_16x16x32_bf16 v[68:71], v[36:39], v[8:11], 0
	s_waitcnt lgkmcnt(1)
	v_mfma_f32_16x16x32_bf16 v[72:75], v[40:43], v[8:11], 0
	s_waitcnt lgkmcnt(0)
	v_mfma_f32_16x16x32_bf16 v[8:11], v[44:47], v[8:11], 0
	v_mfma_f32_16x16x32_bf16 v[16:19], v[16:19], v[12:15], 0
	v_mfma_f32_16x16x32_bf16 v[20:23], v[20:23], v[12:15], 0
	v_mfma_f32_16x16x32_bf16 v[24:27], v[24:27], v[12:15], 0
	v_mfma_f32_16x16x32_bf16 v[28:31], v[28:31], v[12:15], 0
	v_mfma_f32_16x16x32_bf16 v[32:35], v[32:35], v[12:15], 0
	v_mfma_f32_16x16x32_bf16 v[36:39], v[36:39], v[12:15], 0
	v_mfma_f32_16x16x32_bf16 v[40:43], v[40:43], v[12:15], 0
	v_mfma_f32_16x16x32_bf16 v[12:15], v[44:47], v[12:15], 0
	ds_read_b128 v[44:47], v237 offset:36928
	ds_read_b128 v[76:79], v237 offset:41280
	ds_read_b128 v[80:83], v181 offset:18496
	ds_read_b128 v[84:87], v181 offset:20800
	ds_read_b128 v[88:91], v181 offset:23104
	ds_read_b128 v[92:95], v181 offset:25408
	ds_read_b128 v[96:99], v181 offset:27712
	ds_read_b128 v[100:103], v181 offset:30016
	ds_read_b128 v[104:107], v181 offset:32320
	ds_read_b128 v[108:111], v181 offset:34624
	s_waitcnt lgkmcnt(7)
	v_mfma_f32_16x16x32_bf16 v[48:51], v[80:83], v[44:47], v[48:51]
	s_waitcnt lgkmcnt(6)
	v_mfma_f32_16x16x32_bf16 v[52:55], v[84:87], v[44:47], v[52:55]
	s_waitcnt lgkmcnt(5)
	v_mfma_f32_16x16x32_bf16 v[56:59], v[88:91], v[44:47], v[56:59]
	s_waitcnt lgkmcnt(4)
	v_mfma_f32_16x16x32_bf16 v[60:63], v[92:95], v[44:47], v[60:63]
	s_waitcnt lgkmcnt(3)
	v_mfma_f32_16x16x32_bf16 v[64:67], v[96:99], v[44:47], v[64:67]
	s_waitcnt lgkmcnt(2)
	v_mfma_f32_16x16x32_bf16 v[68:71], v[100:103], v[44:47], v[68:71]
	s_waitcnt lgkmcnt(1)
	v_mfma_f32_16x16x32_bf16 v[72:75], v[104:107], v[44:47], v[72:75]
	s_waitcnt lgkmcnt(0)
	v_mfma_f32_16x16x32_bf16 v[8:11], v[108:111], v[44:47], v[8:11]
	v_mfma_f32_16x16x32_bf16 v[16:19], v[80:83], v[76:79], v[16:19]
	v_mfma_f32_16x16x32_bf16 v[20:23], v[84:87], v[76:79], v[20:23]
	v_mfma_f32_16x16x32_bf16 v[24:27], v[88:91], v[76:79], v[24:27]
	v_mfma_f32_16x16x32_bf16 v[28:31], v[92:95], v[76:79], v[28:31]
	v_mfma_f32_16x16x32_bf16 v[32:35], v[96:99], v[76:79], v[32:35]
	v_mfma_f32_16x16x32_bf16 v[36:39], v[100:103], v[76:79], v[36:39]
	v_mfma_f32_16x16x32_bf16 v[40:43], v[104:107], v[76:79], v[40:43]
	v_mfma_f32_16x16x32_bf16 v[12:15], v[108:111], v[76:79], v[12:15]
	global_load_dwordx4 v[44:47], v[2:3], off offset:128
	s_nop 0
	global_load_dwordx4 v[2:5], v[4:5], off offset:128
	s_nop 0
	global_load_dwordx4 v[76:79], v[6:7], off offset:128
	global_load_dwordx4 v[80:83], v[0:1], off offset:128
	s_barrier
	s_waitcnt vmcnt(3)
	ds_write_b128 v236, v[44:47] offset:18432
	s_waitcnt vmcnt(2)
	ds_write_b128 v236, v[2:5] offset:23040
	s_waitcnt vmcnt(1)
	ds_write_b128 v236, v[76:79] offset:27648
	s_waitcnt vmcnt(0)
	ds_write_b128 v236, v[80:83] offset:32256
	s_waitcnt lgkmcnt(0)
	s_barrier
	ds_read_b128 v[0:3], v237 offset:36992
	ds_read_b128 v[4:7], v237 offset:41344
	ds_read_b128 v[44:47], v181 offset:18432
	ds_read_b128 v[76:79], v181 offset:20736
	ds_read_b128 v[80:83], v181 offset:23040
	ds_read_b128 v[84:87], v181 offset:25344
	ds_read_b128 v[88:91], v181 offset:27648
	ds_read_b128 v[92:95], v181 offset:29952
	ds_read_b128 v[96:99], v181 offset:32256
	ds_read_b128 v[100:103], v181 offset:34560
	s_waitcnt lgkmcnt(3)
	v_mfma_f32_16x16x32_bf16 v[64:67], v[88:91], v[0:3], v[64:67]
	v_mfma_f32_16x16x32_bf16 v[60:63], v[84:87], v[0:3], v[60:63]
	s_waitcnt lgkmcnt(2)
	v_mfma_f32_16x16x32_bf16 v[68:71], v[92:95], v[0:3], v[68:71]
	s_waitcnt lgkmcnt(1)
	v_mfma_f32_16x16x32_bf16 v[72:75], v[96:99], v[0:3], v[72:75]
	v_mfma_f32_16x16x32_bf16 v[84:87], v[84:87], v[4:7], v[28:31]
	v_mfma_f32_16x16x32_bf16 v[88:91], v[88:91], v[4:7], v[32:35]
	v_mfma_f32_16x16x32_bf16 v[92:95], v[92:95], v[4:7], v[36:39]
	v_mfma_f32_16x16x32_bf16 v[96:99], v[96:99], v[4:7], v[40:43]
	ds_read_b128 v[28:31], v237 offset:37056
	ds_read_b128 v[108:111], v237 offset:41408
	ds_read_b128 v[32:35], v181 offset:18496
	ds_read_b128 v[36:39], v181 offset:20800
	ds_read_b128 v[40:43], v181 offset:23104
	ds_read_b128 v[112:115], v181 offset:25408
	ds_read_b128 v[116:119], v181 offset:27712
	ds_read_b128 v[120:123], v181 offset:30016
	ds_read_b128 v[242:245], v181 offset:32320
	ds_read_b128 v[246:249], v181 offset:34624
	v_mfma_f32_16x16x32_bf16 v[48:51], v[44:47], v[0:3], v[48:51]
	v_mfma_f32_16x16x32_bf16 v[44:47], v[44:47], v[4:7], v[16:19]
	s_waitcnt lgkmcnt(3)
	v_mfma_f32_16x16x32_bf16 v[16:19], v[116:119], v[28:31], v[64:67]
	s_nop 2
	global_load_dwordx4 v[64:67], v[158:159], off
	v_mfma_f32_16x16x32_bf16 v[52:55], v[76:79], v[0:3], v[52:55]
	v_mfma_f32_16x16x32_bf16 v[76:79], v[76:79], v[4:7], v[20:23]
	s_waitcnt lgkmcnt(2)
	v_mfma_f32_16x16x32_bf16 v[20:23], v[120:123], v[28:31], v[68:71]
	s_nop 2
	ds_read_b32 v68, v229
	v_mfma_f32_16x16x32_bf16 v[56:59], v[80:83], v[0:3], v[56:59]
	s_waitcnt vmcnt(0)
	v_lshlrev_b32_e32 v70, 16, v64
	v_mfma_f32_16x16x32_bf16 v[80:83], v[80:83], v[4:7], v[24:27]
	v_and_b32_e32 v71, 0xffff0000, v64
	v_mfma_f32_16x16x32_bf16 v[104:107], v[100:103], v[0:3], v[8:11]
	v_mfma_f32_16x16x32_bf16 v[100:103], v[100:103], v[4:7], v[12:15]
	v_mfma_f32_16x16x32_bf16 v[4:7], v[36:39], v[28:31], v[52:55]
	v_mfma_f32_16x16x32_bf16 v[8:11], v[40:43], v[28:31], v[56:59]
	s_waitcnt lgkmcnt(2)
	v_mfma_f32_16x16x32_bf16 v[24:27], v[242:245], v[28:31], v[72:75]
	v_mfma_f32_16x16x32_bf16 v[36:39], v[36:39], v[108:111], v[76:79]
	s_nop 1
	ds_read_b32 v72, v230
	ds_read_b32 v76, v231
	v_mfma_f32_16x16x32_bf16 v[40:43], v[40:43], v[108:111], v[80:83]
	s_nop 2
	ds_read_b32 v82, v232
	s_waitcnt lgkmcnt(3)
	v_pk_mul_f32 v[70:71], v[68:69], v[70:71] op_sel_hi:[0,1]
	v_cvt_pk_bf16_f32 v64, v70, v71
	v_lshlrev_b32_e32 v70, 16, v65
	v_and_b32_e32 v71, 0xffff0000, v65
	v_pk_mul_f32 v[70:71], v[68:69], v[70:71] op_sel_hi:[0,1]
	v_cvt_pk_bf16_f32 v65, v70, v71
	v_lshlrev_b32_e32 v70, 16, v66
	v_and_b32_e32 v71, 0xffff0000, v66
	v_pk_mul_f32 v[70:71], v[68:69], v[70:71] op_sel_hi:[0,1]
	v_cvt_pk_bf16_f32 v66, v70, v71
	v_lshlrev_b32_e32 v70, 16, v67
	v_and_b32_e32 v71, 0xffff0000, v67
	v_pk_mul_f32 v[68:69], v[68:69], v[70:71] op_sel_hi:[0,1]
	v_cvt_pk_bf16_f32 v67, v68, v69
	global_load_dwordx4 v[68:71], v[160:161], off
	v_mfma_f32_16x16x32_bf16 v[0:3], v[32:35], v[28:31], v[48:51]
	v_lshl_add_u64 v[80:81], v[150:151], 0, s[0:1]
	s_add_i32 s0, s4, 0x318
	s_ashr_i32 s1, s0, 31
	v_mfma_f32_16x16x32_bf16 v[32:35], v[32:35], v[108:111], v[44:47]
	s_lshl_b64 s[0:1], s[0:1], 15
	s_waitcnt vmcnt(0)
	v_lshlrev_b32_e32 v74, 16, v68
	v_and_b32_e32 v75, 0xffff0000, v68
	s_waitcnt lgkmcnt(2)
	v_pk_mul_f32 v[74:75], v[72:73], v[74:75] op_sel_hi:[0,1]
	v_cvt_pk_bf16_f32 v68, v74, v75
	v_lshlrev_b32_e32 v74, 16, v69
	v_and_b32_e32 v75, 0xffff0000, v69
	v_pk_mul_f32 v[74:75], v[72:73], v[74:75] op_sel_hi:[0,1]
	v_cvt_pk_bf16_f32 v69, v74, v75
	v_lshlrev_b32_e32 v74, 16, v70
	v_and_b32_e32 v75, 0xffff0000, v70
	v_pk_mul_f32 v[74:75], v[72:73], v[74:75] op_sel_hi:[0,1]
	v_cvt_pk_bf16_f32 v70, v74, v75
	v_lshlrev_b32_e32 v74, 16, v71
	v_and_b32_e32 v75, 0xffff0000, v71
	v_pk_mul_f32 v[72:73], v[72:73], v[74:75] op_sel_hi:[0,1]
	v_cvt_pk_bf16_f32 v71, v72, v73
	global_load_dwordx4 v[72:75], v[162:163], off
	v_mfma_f32_16x16x32_bf16 v[44:47], v[112:115], v[108:111], v[84:87]
	s_waitcnt vmcnt(0)
	v_lshlrev_b32_e32 v78, 16, v72
	v_and_b32_e32 v79, 0xffff0000, v72
	s_waitcnt lgkmcnt(1)
	v_pk_mul_f32 v[78:79], v[76:77], v[78:79] op_sel_hi:[0,1]
	v_cvt_pk_bf16_f32 v72, v78, v79
	v_lshlrev_b32_e32 v78, 16, v73
	v_and_b32_e32 v79, 0xffff0000, v73
	v_pk_mul_f32 v[78:79], v[76:77], v[78:79] op_sel_hi:[0,1]
	v_cvt_pk_bf16_f32 v73, v78, v79
	v_lshlrev_b32_e32 v78, 16, v74
	v_and_b32_e32 v79, 0xffff0000, v74
	v_pk_mul_f32 v[78:79], v[76:77], v[78:79] op_sel_hi:[0,1]
	v_cvt_pk_bf16_f32 v74, v78, v79
	v_lshlrev_b32_e32 v78, 16, v75
	v_and_b32_e32 v79, 0xffff0000, v75
	v_pk_mul_f32 v[76:77], v[76:77], v[78:79] op_sel_hi:[0,1]
	v_cvt_pk_bf16_f32 v75, v76, v77
	global_load_dwordx4 v[76:79], v[164:165], off
	v_mfma_f32_16x16x32_bf16 v[56:59], v[242:245], v[108:111], v[96:99]
	s_waitcnt vmcnt(0)
	v_lshlrev_b32_e32 v84, 16, v76
	v_and_b32_e32 v85, 0xffff0000, v76
	s_waitcnt lgkmcnt(0)
	v_pk_mul_f32 v[84:85], v[82:83], v[84:85] op_sel_hi:[0,1]
	v_cvt_pk_bf16_f32 v76, v84, v85
	v_lshlrev_b32_e32 v84, 16, v77
	v_and_b32_e32 v85, 0xffff0000, v77
	v_pk_mul_f32 v[84:85], v[82:83], v[84:85] op_sel_hi:[0,1]
	v_cvt_pk_bf16_f32 v77, v84, v85
	v_lshlrev_b32_e32 v84, 16, v78
	v_and_b32_e32 v85, 0xffff0000, v78
	v_pk_mul_f32 v[84:85], v[82:83], v[84:85] op_sel_hi:[0,1]
	v_cvt_pk_bf16_f32 v78, v84, v85
	v_lshlrev_b32_e32 v84, 16, v79
	v_and_b32_e32 v85, 0xffff0000, v79
	v_lshl_add_u64 v[96:97], v[80:81], 0, v[138:139]
	v_pk_mul_f32 v[82:83], v[82:83], v[84:85] op_sel_hi:[0,1]
	v_mfma_f32_16x16x32_bf16 v[12:15], v[112:115], v[28:31], v[60:63]
	v_lshl_add_u64 v[98:99], v[80:81], 0, v[140:141]
	v_cvt_pk_bf16_f32 v79, v82, v83
	v_mfma_f32_16x16x32_bf16 v[48:51], v[116:119], v[108:111], v[88:91]
	v_mfma_f32_16x16x32_bf16 v[52:55], v[120:123], v[108:111], v[92:95]
	v_mfma_f32_16x16x32_bf16 v[60:63], v[246:249], v[108:111], v[100:103]
	s_nop 2
	v_lshl_add_u64 v[100:101], v[80:81], 0, v[142:143]
	v_lshl_add_u64 v[102:103], v[80:81], 0, v[146:147]
	global_load_dwordx4 v[92:95], v[96:97], off
	global_load_dwordx4 v[88:91], v[98:99], off
	global_load_dwordx4 v[84:87], v[100:101], off
	global_load_dwordx4 v[80:83], v[102:103], off
	s_barrier
	ds_write_b128 v180, v[64:67]
	s_waitcnt vmcnt(3)
	ds_write_b128 v180, v[92:95] offset:18432
	ds_write_b128 v180, v[68:71] offset:4608
	s_waitcnt vmcnt(2)
	ds_write_b128 v180, v[88:91] offset:23040
	ds_write_b128 v180, v[72:75] offset:9216
	s_waitcnt vmcnt(1)
	ds_write_b128 v180, v[84:87] offset:27648
	ds_write_b128 v180, v[76:79] offset:13824
	s_waitcnt vmcnt(0)
	ds_write_b128 v180, v[80:83] offset:32256
	s_waitcnt lgkmcnt(0)
	s_barrier
	global_load_dwordx4 v[64:67], v[164:165], off offset:128
	global_load_dwordx4 v[68:71], v[162:163], off offset:128
	global_load_dwordx4 v[72:75], v[160:161], off offset:128
	global_load_dwordx4 v[76:79], v[158:159], off offset:128
	ds_read_b32 v84, v232
	ds_read_b32 v86, v231
	ds_read_b32 v88, v230
	ds_read_b32 v90, v229
	v_mfma_f32_16x16x32_bf16 v[28:31], v[246:249], v[28:31], v[104:107]
	s_waitcnt vmcnt(3)
	v_lshlrev_b32_e32 v92, 16, v67
	v_and_b32_e32 v93, 0xffff0000, v67
	s_waitcnt lgkmcnt(3)
	v_pk_mul_f32 v[92:93], v[84:85], v[92:93] op_sel_hi:[0,1]
	v_cvt_pk_bf16_f32 v67, v92, v93
	v_lshlrev_b32_e32 v92, 16, v66
	v_and_b32_e32 v93, 0xffff0000, v66
	v_pk_mul_f32 v[92:93], v[84:85], v[92:93] op_sel_hi:[0,1]
	v_cvt_pk_bf16_f32 v66, v92, v93
	v_lshlrev_b32_e32 v92, 16, v65
	v_and_b32_e32 v93, 0xffff0000, v65
	v_pk_mul_f32 v[92:93], v[84:85], v[92:93] op_sel_hi:[0,1]
	v_cvt_pk_bf16_f32 v65, v92, v93
	v_lshlrev_b32_e32 v92, 16, v64
	v_and_b32_e32 v93, 0xffff0000, v64
	v_pk_mul_f32 v[84:85], v[84:85], v[92:93] op_sel_hi:[0,1]
	v_cvt_pk_bf16_f32 v64, v84, v85
	s_waitcnt vmcnt(2)
	v_lshlrev_b32_e32 v92, 16, v71
	v_and_b32_e32 v93, 0xffff0000, v71
	s_waitcnt lgkmcnt(2)
	v_pk_mul_f32 v[92:93], v[86:87], v[92:93] op_sel_hi:[0,1]
	v_cvt_pk_bf16_f32 v71, v92, v93
	v_lshlrev_b32_e32 v92, 16, v70
	v_and_b32_e32 v93, 0xffff0000, v70
	v_pk_mul_f32 v[92:93], v[86:87], v[92:93] op_sel_hi:[0,1]
	v_cvt_pk_bf16_f32 v70, v92, v93
	v_lshlrev_b32_e32 v92, 16, v69
	v_and_b32_e32 v93, 0xffff0000, v69
	v_pk_mul_f32 v[92:93], v[86:87], v[92:93] op_sel_hi:[0,1]
	v_cvt_pk_bf16_f32 v69, v92, v93
	v_lshlrev_b32_e32 v92, 16, v68
	v_and_b32_e32 v93, 0xffff0000, v68
	v_pk_mul_f32 v[86:87], v[86:87], v[92:93] op_sel_hi:[0,1]
	v_cvt_pk_bf16_f32 v68, v86, v87
	s_waitcnt vmcnt(1)
	v_lshlrev_b32_e32 v92, 16, v75
	v_and_b32_e32 v93, 0xffff0000, v75
	s_waitcnt lgkmcnt(1)
	v_pk_mul_f32 v[92:93], v[88:89], v[92:93] op_sel_hi:[0,1]
	v_cvt_pk_bf16_f32 v75, v92, v93
	v_lshlrev_b32_e32 v92, 16, v74
	v_and_b32_e32 v93, 0xffff0000, v74
	v_pk_mul_f32 v[92:93], v[88:89], v[92:93] op_sel_hi:[0,1]
	v_cvt_pk_bf16_f32 v74, v92, v93
	v_lshlrev_b32_e32 v92, 16, v73
	v_and_b32_e32 v93, 0xffff0000, v73
	v_pk_mul_f32 v[92:93], v[88:89], v[92:93] op_sel_hi:[0,1]
	v_cvt_pk_bf16_f32 v73, v92, v93
	v_lshlrev_b32_e32 v92, 16, v72
	v_and_b32_e32 v93, 0xffff0000, v72
	v_pk_mul_f32 v[88:89], v[88:89], v[92:93] op_sel_hi:[0,1]
	v_cvt_pk_bf16_f32 v72, v88, v89
	s_waitcnt vmcnt(0)
	v_lshlrev_b32_e32 v92, 16, v79
	v_and_b32_e32 v93, 0xffff0000, v79
	s_waitcnt lgkmcnt(0)
	v_pk_mul_f32 v[92:93], v[90:91], v[92:93] op_sel_hi:[0,1]
	v_cvt_pk_bf16_f32 v79, v92, v93
	v_lshlrev_b32_e32 v92, 16, v78
	v_and_b32_e32 v93, 0xffff0000, v78
	v_pk_mul_f32 v[92:93], v[90:91], v[92:93] op_sel_hi:[0,1]
	v_cvt_pk_bf16_f32 v78, v92, v93
	v_lshlrev_b32_e32 v92, 16, v77
	v_and_b32_e32 v93, 0xffff0000, v77
	v_pk_mul_f32 v[92:93], v[90:91], v[92:93] op_sel_hi:[0,1]
	v_cvt_pk_bf16_f32 v77, v92, v93
	v_lshlrev_b32_e32 v92, 16, v76
	v_and_b32_e32 v93, 0xffff0000, v76
	v_pk_mul_f32 v[90:91], v[90:91], v[92:93] op_sel_hi:[0,1]
	v_cvt_pk_bf16_f32 v76, v90, v91
	ds_read_b128 v[84:87], v241
	ds_read_b128 v[80:83], v241 offset:2304
	ds_read_b128 v[88:91], v181 offset:18432
	ds_read_b128 v[92:95], v181 offset:20736
	ds_read_b128 v[104:107], v181 offset:23040
	ds_read_b128 v[108:111], v181 offset:25344
	ds_read_b128 v[112:115], v181 offset:27648
	ds_read_b128 v[116:119], v181 offset:29952
	ds_read_b128 v[120:123], v181 offset:32256
	ds_read_b128 v[242:245], v181 offset:34560
	s_waitcnt lgkmcnt(7)
	v_mfma_f32_16x16x32_bf16 v[0:3], v[88:91], v[84:87], v[0:3]
	s_waitcnt lgkmcnt(6)
	v_mfma_f32_16x16x32_bf16 v[4:7], v[92:95], v[84:87], v[4:7]
	s_waitcnt lgkmcnt(5)
	v_mfma_f32_16x16x32_bf16 v[8:11], v[104:107], v[84:87], v[8:11]
	s_waitcnt lgkmcnt(4)
	v_mfma_f32_16x16x32_bf16 v[12:15], v[108:111], v[84:87], v[12:15]
	s_waitcnt lgkmcnt(3)
	v_mfma_f32_16x16x32_bf16 v[16:19], v[112:115], v[84:87], v[16:19]
	s_waitcnt lgkmcnt(2)
	v_mfma_f32_16x16x32_bf16 v[20:23], v[116:119], v[84:87], v[20:23]
	s_waitcnt lgkmcnt(1)
	v_mfma_f32_16x16x32_bf16 v[24:27], v[120:123], v[84:87], v[24:27]
	s_waitcnt lgkmcnt(0)
	v_mfma_f32_16x16x32_bf16 v[28:31], v[242:245], v[84:87], v[28:31]
	v_mfma_f32_16x16x32_bf16 v[32:35], v[88:91], v[80:83], v[32:35]
	v_mfma_f32_16x16x32_bf16 v[36:39], v[92:95], v[80:83], v[36:39]
	v_mfma_f32_16x16x32_bf16 v[40:43], v[104:107], v[80:83], v[40:43]
	v_mfma_f32_16x16x32_bf16 v[44:47], v[108:111], v[80:83], v[44:47]
	v_mfma_f32_16x16x32_bf16 v[48:51], v[112:115], v[80:83], v[48:51]
	v_mfma_f32_16x16x32_bf16 v[52:55], v[116:119], v[80:83], v[52:55]
	v_mfma_f32_16x16x32_bf16 v[56:59], v[120:123], v[80:83], v[56:59]
	v_mfma_f32_16x16x32_bf16 v[60:63], v[242:245], v[80:83], v[60:63]
	ds_read_b128 v[80:83], v241 offset:64
	ds_read_b128 v[84:87], v241 offset:2368
	ds_read_b128 v[88:91], v181 offset:18496
	ds_read_b128 v[92:95], v181 offset:20800
	ds_read_b128 v[104:107], v181 offset:23104
	ds_read_b128 v[108:111], v181 offset:25408
	ds_read_b128 v[112:115], v181 offset:27712
	ds_read_b128 v[116:119], v181 offset:30016
	ds_read_b128 v[120:123], v181 offset:32320
	ds_read_b128 v[242:245], v181 offset:34624
	s_waitcnt lgkmcnt(7)
	v_mfma_f32_16x16x32_bf16 v[0:3], v[88:91], v[80:83], v[0:3]
	s_waitcnt lgkmcnt(6)
	v_mfma_f32_16x16x32_bf16 v[4:7], v[92:95], v[80:83], v[4:7]
	s_waitcnt lgkmcnt(5)
	v_mfma_f32_16x16x32_bf16 v[8:11], v[104:107], v[80:83], v[8:11]
	s_waitcnt lgkmcnt(4)
	v_mfma_f32_16x16x32_bf16 v[12:15], v[108:111], v[80:83], v[12:15]
	s_waitcnt lgkmcnt(3)
	v_mfma_f32_16x16x32_bf16 v[16:19], v[112:115], v[80:83], v[16:19]
	s_waitcnt lgkmcnt(2)
	v_mfma_f32_16x16x32_bf16 v[20:23], v[116:119], v[80:83], v[20:23]
	s_waitcnt lgkmcnt(1)
	v_mfma_f32_16x16x32_bf16 v[24:27], v[120:123], v[80:83], v[24:27]
	s_waitcnt lgkmcnt(0)
	v_mfma_f32_16x16x32_bf16 v[28:31], v[242:245], v[80:83], v[28:31]
	v_mfma_f32_16x16x32_bf16 v[32:35], v[88:91], v[84:87], v[32:35]
	v_mfma_f32_16x16x32_bf16 v[36:39], v[92:95], v[84:87], v[36:39]
	v_mfma_f32_16x16x32_bf16 v[40:43], v[104:107], v[84:87], v[40:43]
	v_mfma_f32_16x16x32_bf16 v[44:47], v[108:111], v[84:87], v[44:47]
	v_mfma_f32_16x16x32_bf16 v[48:51], v[112:115], v[84:87], v[48:51]
	v_mfma_f32_16x16x32_bf16 v[52:55], v[116:119], v[84:87], v[52:55]
	v_mfma_f32_16x16x32_bf16 v[56:59], v[120:123], v[84:87], v[56:59]
	v_mfma_f32_16x16x32_bf16 v[60:63], v[242:245], v[84:87], v[60:63]
	global_load_dwordx4 v[92:95], v[96:97], off offset:128
	global_load_dwordx4 v[88:91], v[98:99], off offset:128
	global_load_dwordx4 v[84:87], v[100:101], off offset:128
	global_load_dwordx4 v[80:83], v[102:103], off offset:128
	s_barrier
	ds_write_b128 v180, v[76:79]
	s_waitcnt vmcnt(3)
	ds_write_b128 v180, v[92:95] offset:18432
	ds_write_b128 v180, v[72:75] offset:4608
	s_waitcnt vmcnt(2)
	ds_write_b128 v180, v[88:91] offset:23040
	ds_write_b128 v180, v[68:71] offset:9216
	s_waitcnt vmcnt(1)
	ds_write_b128 v180, v[84:87] offset:27648
	ds_write_b128 v180, v[64:67] offset:13824
	s_waitcnt vmcnt(0)
	ds_write_b128 v180, v[80:83] offset:32256
	s_waitcnt lgkmcnt(0)
	s_barrier
	ds_read_b128 v[64:67], v181 offset:34560
	ds_read_b128 v[68:71], v181 offset:32256
	ds_read_b128 v[72:75], v181 offset:29952
	ds_read_b128 v[76:79], v181 offset:27648
	ds_read_b128 v[80:83], v181 offset:25344
	ds_read_b128 v[84:87], v181 offset:23040
	ds_read_b128 v[88:91], v181 offset:20736
	ds_read_b128 v[92:95], v181 offset:18432
	ds_read_b128 v[96:99], v241 offset:2304
	ds_read_b128 v[100:103], v241
	s_waitcnt lgkmcnt(0)
	v_mfma_f32_16x16x32_bf16 v[0:3], v[92:95], v[100:103], v[0:3]
	v_mfma_f32_16x16x32_bf16 v[4:7], v[88:91], v[100:103], v[4:7]
	v_mfma_f32_16x16x32_bf16 v[8:11], v[84:87], v[100:103], v[8:11]
	v_mfma_f32_16x16x32_bf16 v[12:15], v[80:83], v[100:103], v[12:15]
	v_mfma_f32_16x16x32_bf16 v[16:19], v[76:79], v[100:103], v[16:19]
	v_mfma_f32_16x16x32_bf16 v[20:23], v[72:75], v[100:103], v[20:23]
	v_mfma_f32_16x16x32_bf16 v[24:27], v[68:71], v[100:103], v[24:27]
	v_mfma_f32_16x16x32_bf16 v[28:31], v[64:67], v[100:103], v[28:31]
	v_mfma_f32_16x16x32_bf16 v[32:35], v[92:95], v[96:99], v[32:35]
	v_mfma_f32_16x16x32_bf16 v[36:39], v[88:91], v[96:99], v[36:39]
	v_mfma_f32_16x16x32_bf16 v[40:43], v[84:87], v[96:99], v[40:43]
	v_mfma_f32_16x16x32_bf16 v[44:47], v[80:83], v[96:99], v[44:47]
	v_mfma_f32_16x16x32_bf16 v[48:51], v[76:79], v[96:99], v[48:51]
	v_mfma_f32_16x16x32_bf16 v[52:55], v[72:75], v[96:99], v[52:55]
	v_mfma_f32_16x16x32_bf16 v[56:59], v[68:71], v[96:99], v[56:59]
	v_mfma_f32_16x16x32_bf16 v[60:63], v[64:67], v[96:99], v[60:63]
	ds_read_b128 v[64:67], v241 offset:64
	ds_read_b128 v[68:71], v241 offset:2368
	ds_read_b128 v[72:75], v181 offset:18496
	ds_read_b128 v[76:79], v181 offset:20800
	ds_read_b128 v[80:83], v181 offset:23104
	ds_read_b128 v[84:87], v181 offset:25408
	ds_read_b128 v[88:91], v181 offset:27712
	ds_read_b128 v[92:95], v181 offset:30016
	ds_read_b128 v[96:99], v181 offset:32320
	ds_read_b128 v[100:103], v181 offset:34624
	s_waitcnt lgkmcnt(7)
	v_mfma_f32_16x16x32_bf16 v[0:3], v[72:75], v[64:67], v[0:3]
	s_waitcnt lgkmcnt(6)
	v_mfma_f32_16x16x32_bf16 v[4:7], v[76:79], v[64:67], v[4:7]
	s_waitcnt lgkmcnt(5)
	v_mfma_f32_16x16x32_bf16 v[8:11], v[80:83], v[64:67], v[8:11]
	s_waitcnt lgkmcnt(4)
	v_mfma_f32_16x16x32_bf16 v[12:15], v[84:87], v[64:67], v[12:15]
	s_waitcnt lgkmcnt(3)
	v_mfma_f32_16x16x32_bf16 v[16:19], v[88:91], v[64:67], v[16:19]
	s_waitcnt lgkmcnt(2)
	v_mfma_f32_16x16x32_bf16 v[20:23], v[92:95], v[64:67], v[20:23]
	s_waitcnt lgkmcnt(1)
	v_mfma_f32_16x16x32_bf16 v[24:27], v[96:99], v[64:67], v[24:27]
	s_waitcnt lgkmcnt(0)
	v_mfma_f32_16x16x32_bf16 v[28:31], v[100:103], v[64:67], v[28:31]
	global_load_dwordx4 v[64:67], v[158:159], off
	v_mfma_f32_16x16x32_bf16 v[32:35], v[72:75], v[68:71], v[32:35]
	ds_read2_b32 v[104:105], v229 offset0:128 offset1:160
	v_mfma_f32_16x16x32_bf16 v[36:39], v[76:79], v[68:71], v[36:39]
	v_mfma_f32_16x16x32_bf16 v[40:43], v[80:83], v[68:71], v[40:43]
	ds_read2_b32 v[106:107], v229 offset0:192 offset1:224
	v_lshl_add_u64 v[80:81], v[150:151], 0, s[0:1]
	v_readlane_b32 s0, v252, 53
	v_mfma_f32_16x16x32_bf16 v[44:47], v[84:87], v[68:71], v[44:47]
	v_readlane_b32 s1, v252, 54
	v_mfma_f32_16x16x32_bf16 v[48:51], v[88:91], v[68:71], v[48:51]
	v_mfma_f32_16x16x32_bf16 v[52:55], v[92:95], v[68:71], v[52:55]
	v_mfma_f32_16x16x32_bf16 v[56:59], v[96:99], v[68:71], v[56:59]
	v_lshl_add_u64 v[96:97], v[80:81], 0, v[138:139]
	v_lshl_add_u64 v[98:99], v[80:81], 0, v[140:141]
	v_mfma_f32_16x16x32_bf16 v[60:63], v[100:103], v[68:71], v[60:63]
	global_load_dwordx4 v[68:71], v[160:161], off
	global_load_dwordx4 v[72:75], v[162:163], off
	global_load_dwordx4 v[76:79], v[164:165], off
	v_lshl_add_u64 v[100:101], v[80:81], 0, v[142:143]
	v_lshl_add_u64 v[102:103], v[80:81], 0, v[146:147]
	s_waitcnt vmcnt(3)
	v_lshlrev_b32_e32 v108, 16, v64
	v_and_b32_e32 v109, 0xffff0000, v64
	s_waitcnt lgkmcnt(1)
	v_pk_mul_f32 v[108:109], v[104:105], v[108:109] op_sel_hi:[0,1]
	v_cvt_pk_bf16_f32 v64, v108, v109
	v_lshlrev_b32_e32 v108, 16, v65
	v_and_b32_e32 v109, 0xffff0000, v65
	v_pk_mul_f32 v[108:109], v[104:105], v[108:109] op_sel_hi:[0,1]
	v_cvt_pk_bf16_f32 v65, v108, v109
	v_lshlrev_b32_e32 v108, 16, v66
	v_and_b32_e32 v109, 0xffff0000, v66
	v_pk_mul_f32 v[108:109], v[104:105], v[108:109] op_sel_hi:[0,1]
	v_cvt_pk_bf16_f32 v66, v108, v109
	v_lshlrev_b32_e32 v108, 16, v67
	v_and_b32_e32 v109, 0xffff0000, v67
	v_pk_mul_f32 v[108:109], v[104:105], v[108:109] op_sel_hi:[0,1]
	v_cvt_pk_bf16_f32 v67, v108, v109
	v_mov_b32_e32 v110, v105
	s_waitcnt vmcnt(2)
	v_lshlrev_b32_e32 v108, 16, v68
	v_and_b32_e32 v109, 0xffff0000, v68
	v_pk_mul_f32 v[108:109], v[110:111], v[108:109] op_sel_hi:[0,1]
	v_cvt_pk_bf16_f32 v68, v108, v109
	v_lshlrev_b32_e32 v108, 16, v69
	v_and_b32_e32 v109, 0xffff0000, v69
	v_pk_mul_f32 v[108:109], v[110:111], v[108:109] op_sel_hi:[0,1]
	v_cvt_pk_bf16_f32 v69, v108, v109
	v_lshlrev_b32_e32 v108, 16, v70
	v_and_b32_e32 v109, 0xffff0000, v70
	v_pk_mul_f32 v[108:109], v[110:111], v[108:109] op_sel_hi:[0,1]
	v_cvt_pk_bf16_f32 v70, v108, v109
	v_lshlrev_b32_e32 v108, 16, v71
	v_and_b32_e32 v109, 0xffff0000, v71
	v_pk_mul_f32 v[110:111], v[110:111], v[108:109] op_sel_hi:[0,1]
	v_cvt_pk_bf16_f32 v71, v110, v111
	s_waitcnt vmcnt(1)
	v_lshlrev_b32_e32 v108, 16, v72
	v_and_b32_e32 v109, 0xffff0000, v72
	s_waitcnt lgkmcnt(0)
	v_pk_mul_f32 v[108:109], v[106:107], v[108:109] op_sel_hi:[0,1]
	v_cvt_pk_bf16_f32 v72, v108, v109
	v_lshlrev_b32_e32 v108, 16, v73
	v_and_b32_e32 v109, 0xffff0000, v73
	v_pk_mul_f32 v[108:109], v[106:107], v[108:109] op_sel_hi:[0,1]
	v_cvt_pk_bf16_f32 v73, v108, v109
	v_lshlrev_b32_e32 v108, 16, v74
	v_and_b32_e32 v109, 0xffff0000, v74
	v_pk_mul_f32 v[108:109], v[106:107], v[108:109] op_sel_hi:[0,1]
	v_cvt_pk_bf16_f32 v74, v108, v109
	v_lshlrev_b32_e32 v108, 16, v75
	v_and_b32_e32 v109, 0xffff0000, v75
	v_pk_mul_f32 v[108:109], v[106:107], v[108:109] op_sel_hi:[0,1]
	v_cvt_pk_bf16_f32 v75, v108, v109
	v_mov_b32_e32 v112, v107
	s_waitcnt vmcnt(0)
	v_lshlrev_b32_e32 v108, 16, v76
	v_and_b32_e32 v109, 0xffff0000, v76
	v_pk_mul_f32 v[108:109], v[112:113], v[108:109] op_sel_hi:[0,1]
	v_cvt_pk_bf16_f32 v76, v108, v109
	v_lshlrev_b32_e32 v108, 16, v77
	v_and_b32_e32 v109, 0xffff0000, v77
	v_pk_mul_f32 v[108:109], v[112:113], v[108:109] op_sel_hi:[0,1]
	v_cvt_pk_bf16_f32 v77, v108, v109
	v_lshlrev_b32_e32 v108, 16, v78
	v_and_b32_e32 v109, 0xffff0000, v78
	v_pk_mul_f32 v[108:109], v[112:113], v[108:109] op_sel_hi:[0,1]
	v_cvt_pk_bf16_f32 v78, v108, v109
	v_lshlrev_b32_e32 v108, 16, v79
	v_and_b32_e32 v109, 0xffff0000, v79
	v_pk_mul_f32 v[112:113], v[112:113], v[108:109] op_sel_hi:[0,1]
	v_cvt_pk_bf16_f32 v79, v112, v113
	global_load_dwordx4 v[92:95], v[96:97], off
	global_load_dwordx4 v[88:91], v[98:99], off
	global_load_dwordx4 v[84:87], v[100:101], off
	global_load_dwordx4 v[80:83], v[102:103], off
	s_barrier
	ds_write_b128 v180, v[64:67]
	s_waitcnt vmcnt(3)
	ds_write_b128 v180, v[92:95] offset:18432
	ds_write_b128 v180, v[68:71] offset:4608
	s_waitcnt vmcnt(2)
	ds_write_b128 v180, v[88:91] offset:23040
	ds_write_b128 v180, v[72:75] offset:9216
	s_waitcnt vmcnt(1)
	ds_write_b128 v180, v[84:87] offset:27648
	ds_write_b128 v180, v[76:79] offset:13824
	s_waitcnt vmcnt(0)
	ds_write_b128 v180, v[80:83] offset:32256
	s_waitcnt lgkmcnt(0)
	s_barrier
	global_load_dwordx4 v[64:67], v[164:165], off offset:128
	global_load_dwordx4 v[68:71], v[162:163], off offset:128
	global_load_dwordx4 v[72:75], v[160:161], off offset:128
	global_load_dwordx4 v[76:79], v[158:159], off offset:128
	ds_read2_b32 v[84:85], v229 offset0:192 offset1:224
	ds_read2_b32 v[86:87], v229 offset0:128 offset1:160
	s_waitcnt lgkmcnt(1)
	v_mov_b32_e32 v88, v85
	s_waitcnt lgkmcnt(0)
	v_mov_b32_e32 v90, v87
	s_waitcnt vmcnt(3)
	v_lshlrev_b32_e32 v92, 16, v67
	v_and_b32_e32 v93, 0xffff0000, v67
	v_pk_mul_f32 v[92:93], v[88:89], v[92:93] op_sel_hi:[0,1]
	v_cvt_pk_bf16_f32 v67, v92, v93
	v_lshlrev_b32_e32 v92, 16, v66
	v_and_b32_e32 v93, 0xffff0000, v66
	v_pk_mul_f32 v[92:93], v[88:89], v[92:93] op_sel_hi:[0,1]
	v_cvt_pk_bf16_f32 v66, v92, v93
	v_lshlrev_b32_e32 v92, 16, v65
	v_and_b32_e32 v93, 0xffff0000, v65
	v_pk_mul_f32 v[92:93], v[88:89], v[92:93] op_sel_hi:[0,1]
	v_cvt_pk_bf16_f32 v65, v92, v93
	v_lshlrev_b32_e32 v92, 16, v64
	v_and_b32_e32 v93, 0xffff0000, v64
	v_pk_mul_f32 v[92:93], v[88:89], v[92:93] op_sel_hi:[0,1]
	v_cvt_pk_bf16_f32 v64, v92, v93
	s_waitcnt vmcnt(2)
	v_lshlrev_b32_e32 v92, 16, v71
	v_and_b32_e32 v93, 0xffff0000, v71
	v_pk_mul_f32 v[92:93], v[84:85], v[92:93] op_sel_hi:[0,1]
	v_cvt_pk_bf16_f32 v71, v92, v93
	v_lshlrev_b32_e32 v92, 16, v70
	v_and_b32_e32 v93, 0xffff0000, v70
	v_pk_mul_f32 v[92:93], v[84:85], v[92:93] op_sel_hi:[0,1]
	v_cvt_pk_bf16_f32 v70, v92, v93
	v_lshlrev_b32_e32 v92, 16, v69
	v_and_b32_e32 v93, 0xffff0000, v69
	v_pk_mul_f32 v[92:93], v[84:85], v[92:93] op_sel_hi:[0,1]
	v_cvt_pk_bf16_f32 v69, v92, v93
	v_lshlrev_b32_e32 v92, 16, v68
	v_and_b32_e32 v93, 0xffff0000, v68
	v_pk_mul_f32 v[84:85], v[84:85], v[92:93] op_sel_hi:[0,1]
	v_cvt_pk_bf16_f32 v68, v84, v85
	s_waitcnt vmcnt(1)
	v_lshlrev_b32_e32 v92, 16, v75
	v_and_b32_e32 v93, 0xffff0000, v75
	v_pk_mul_f32 v[92:93], v[90:91], v[92:93] op_sel_hi:[0,1]
	v_cvt_pk_bf16_f32 v75, v92, v93
	v_lshlrev_b32_e32 v92, 16, v74
	v_and_b32_e32 v93, 0xffff0000, v74
	v_pk_mul_f32 v[92:93], v[90:91], v[92:93] op_sel_hi:[0,1]
	v_cvt_pk_bf16_f32 v74, v92, v93
	v_lshlrev_b32_e32 v92, 16, v73
	v_and_b32_e32 v93, 0xffff0000, v73
	v_pk_mul_f32 v[92:93], v[90:91], v[92:93] op_sel_hi:[0,1]
	v_cvt_pk_bf16_f32 v73, v92, v93
	v_lshlrev_b32_e32 v92, 16, v72
	v_and_b32_e32 v93, 0xffff0000, v72
	v_pk_mul_f32 v[92:93], v[90:91], v[92:93] op_sel_hi:[0,1]
	v_cvt_pk_bf16_f32 v72, v92, v93
	s_waitcnt vmcnt(0)
	v_lshlrev_b32_e32 v92, 16, v79
	v_and_b32_e32 v93, 0xffff0000, v79
	v_pk_mul_f32 v[92:93], v[86:87], v[92:93] op_sel_hi:[0,1]
	v_cvt_pk_bf16_f32 v79, v92, v93
	v_lshlrev_b32_e32 v92, 16, v78
	v_and_b32_e32 v93, 0xffff0000, v78
	v_pk_mul_f32 v[92:93], v[86:87], v[92:93] op_sel_hi:[0,1]
	v_cvt_pk_bf16_f32 v78, v92, v93
	v_lshlrev_b32_e32 v92, 16, v77
	v_and_b32_e32 v93, 0xffff0000, v77
	v_pk_mul_f32 v[92:93], v[86:87], v[92:93] op_sel_hi:[0,1]
	v_cvt_pk_bf16_f32 v77, v92, v93
	v_lshlrev_b32_e32 v92, 16, v76
	v_and_b32_e32 v93, 0xffff0000, v76
	v_pk_mul_f32 v[86:87], v[86:87], v[92:93] op_sel_hi:[0,1]
	v_cvt_pk_bf16_f32 v76, v86, v87
	ds_read_b128 v[84:87], v241
	ds_read_b128 v[80:83], v241 offset:2304
	ds_read_b128 v[88:91], v181 offset:18432
	ds_read_b128 v[92:95], v181 offset:20736
	ds_read_b128 v[104:107], v181 offset:23040
	ds_read_b128 v[108:111], v181 offset:25344
	ds_read_b128 v[112:115], v181 offset:27648
	ds_read_b128 v[116:119], v181 offset:29952
	ds_read_b128 v[120:123], v181 offset:32256
	ds_read_b128 v[158:161], v181 offset:34560
	s_waitcnt lgkmcnt(7)
	v_mfma_f32_16x16x32_bf16 v[0:3], v[88:91], v[84:87], v[0:3]
	s_waitcnt lgkmcnt(6)
	v_mfma_f32_16x16x32_bf16 v[4:7], v[92:95], v[84:87], v[4:7]
	s_waitcnt lgkmcnt(5)
	v_mfma_f32_16x16x32_bf16 v[8:11], v[104:107], v[84:87], v[8:11]
	s_waitcnt lgkmcnt(4)
	v_mfma_f32_16x16x32_bf16 v[12:15], v[108:111], v[84:87], v[12:15]
	s_waitcnt lgkmcnt(3)
	v_mfma_f32_16x16x32_bf16 v[16:19], v[112:115], v[84:87], v[16:19]
	s_waitcnt lgkmcnt(2)
	v_mfma_f32_16x16x32_bf16 v[20:23], v[116:119], v[84:87], v[20:23]
	s_waitcnt lgkmcnt(1)
	v_mfma_f32_16x16x32_bf16 v[24:27], v[120:123], v[84:87], v[24:27]
	s_waitcnt lgkmcnt(0)
	v_mfma_f32_16x16x32_bf16 v[28:31], v[158:161], v[84:87], v[28:31]
	v_mfma_f32_16x16x32_bf16 v[32:35], v[88:91], v[80:83], v[32:35]
	v_mfma_f32_16x16x32_bf16 v[36:39], v[92:95], v[80:83], v[36:39]
	v_mfma_f32_16x16x32_bf16 v[40:43], v[104:107], v[80:83], v[40:43]
	v_mfma_f32_16x16x32_bf16 v[44:47], v[108:111], v[80:83], v[44:47]
	v_mfma_f32_16x16x32_bf16 v[48:51], v[112:115], v[80:83], v[48:51]
	v_mfma_f32_16x16x32_bf16 v[52:55], v[116:119], v[80:83], v[52:55]
	v_mfma_f32_16x16x32_bf16 v[56:59], v[120:123], v[80:83], v[56:59]
	v_mfma_f32_16x16x32_bf16 v[60:63], v[158:161], v[80:83], v[60:63]
	ds_read_b128 v[80:83], v241 offset:64
	ds_read_b128 v[84:87], v241 offset:2368
	ds_read_b128 v[88:91], v181 offset:18496
	ds_read_b128 v[92:95], v181 offset:20800
	ds_read_b128 v[104:107], v181 offset:23104
	ds_read_b128 v[108:111], v181 offset:25408
	ds_read_b128 v[112:115], v181 offset:27712
	ds_read_b128 v[116:119], v181 offset:30016
	ds_read_b128 v[120:123], v181 offset:32320
	ds_read_b128 v[158:161], v181 offset:34624
	s_waitcnt lgkmcnt(7)
	v_mfma_f32_16x16x32_bf16 v[0:3], v[88:91], v[80:83], v[0:3]
	s_waitcnt lgkmcnt(6)
	v_mfma_f32_16x16x32_bf16 v[4:7], v[92:95], v[80:83], v[4:7]
	s_waitcnt lgkmcnt(5)
	v_mfma_f32_16x16x32_bf16 v[8:11], v[104:107], v[80:83], v[8:11]
	s_waitcnt lgkmcnt(4)
	v_mfma_f32_16x16x32_bf16 v[12:15], v[108:111], v[80:83], v[12:15]
	s_waitcnt lgkmcnt(3)
	v_mfma_f32_16x16x32_bf16 v[16:19], v[112:115], v[80:83], v[16:19]
	s_waitcnt lgkmcnt(2)
	v_mfma_f32_16x16x32_bf16 v[20:23], v[116:119], v[80:83], v[20:23]
	s_waitcnt lgkmcnt(1)
	v_mfma_f32_16x16x32_bf16 v[24:27], v[120:123], v[80:83], v[24:27]
	s_waitcnt lgkmcnt(0)
	v_mfma_f32_16x16x32_bf16 v[28:31], v[158:161], v[80:83], v[28:31]
	v_mfma_f32_16x16x32_bf16 v[32:35], v[88:91], v[84:87], v[32:35]
	v_mfma_f32_16x16x32_bf16 v[36:39], v[92:95], v[84:87], v[36:39]
	v_mfma_f32_16x16x32_bf16 v[40:43], v[104:107], v[84:87], v[40:43]
	v_mfma_f32_16x16x32_bf16 v[44:47], v[108:111], v[84:87], v[44:47]
	v_mfma_f32_16x16x32_bf16 v[48:51], v[112:115], v[84:87], v[48:51]
	v_mfma_f32_16x16x32_bf16 v[52:55], v[116:119], v[84:87], v[52:55]
	v_mfma_f32_16x16x32_bf16 v[56:59], v[120:123], v[84:87], v[56:59]
	v_mfma_f32_16x16x32_bf16 v[60:63], v[158:161], v[84:87], v[60:63]
	global_load_dwordx4 v[92:95], v[96:97], off offset:128
	global_load_dwordx4 v[88:91], v[98:99], off offset:128
	global_load_dwordx4 v[84:87], v[100:101], off offset:128
	global_load_dwordx4 v[80:83], v[102:103], off offset:128
	s_barrier
	ds_write_b128 v180, v[76:79]
	s_waitcnt vmcnt(3)
	ds_write_b128 v180, v[92:95] offset:18432
	ds_write_b128 v180, v[72:75] offset:4608
	s_waitcnt vmcnt(2)
	ds_write_b128 v180, v[88:91] offset:23040
	ds_write_b128 v180, v[68:71] offset:9216
	s_waitcnt vmcnt(1)
	ds_write_b128 v180, v[84:87] offset:27648
	ds_write_b128 v180, v[64:67] offset:13824
	s_waitcnt vmcnt(0)
	ds_write_b128 v180, v[80:83] offset:32256
	s_waitcnt lgkmcnt(0)
	s_barrier
	ds_read_b128 v[64:67], v181 offset:34560
	ds_read_b128 v[68:71], v181 offset:32256
	ds_read_b128 v[72:75], v181 offset:29952
	ds_read_b128 v[76:79], v181 offset:27648
	ds_read_b128 v[80:83], v181 offset:25344
	ds_read_b128 v[84:87], v181 offset:23040
	ds_read_b128 v[88:91], v181 offset:20736
	ds_read_b128 v[92:95], v181 offset:18432
	ds_read_b128 v[96:99], v241 offset:2304
	ds_read_b128 v[100:103], v241
	s_waitcnt lgkmcnt(0)
	v_mfma_f32_16x16x32_bf16 v[8:11], v[84:87], v[100:103], v[8:11]
	v_mfma_f32_16x16x32_bf16 v[12:15], v[80:83], v[100:103], v[12:15]
	v_mfma_f32_16x16x32_bf16 v[16:19], v[76:79], v[100:103], v[16:19]
	v_mfma_f32_16x16x32_bf16 v[20:23], v[72:75], v[100:103], v[20:23]
	v_mfma_f32_16x16x32_bf16 v[84:87], v[84:87], v[96:99], v[40:43]
	v_mfma_f32_16x16x32_bf16 v[76:79], v[76:79], v[96:99], v[48:51]
	v_mfma_f32_16x16x32_bf16 v[0:3], v[92:95], v[100:103], v[0:3]
	v_mfma_f32_16x16x32_bf16 v[4:7], v[88:91], v[100:103], v[4:7]
	v_mfma_f32_16x16x32_bf16 v[24:27], v[68:71], v[100:103], v[24:27]
	v_mfma_f32_16x16x32_bf16 v[28:31], v[64:67], v[100:103], v[28:31]
	v_mfma_f32_16x16x32_bf16 v[92:95], v[92:95], v[96:99], v[32:35]
	v_mfma_f32_16x16x32_bf16 v[88:91], v[88:91], v[96:99], v[36:39]
	v_mfma_f32_16x16x32_bf16 v[80:83], v[80:83], v[96:99], v[44:47]
	v_mfma_f32_16x16x32_bf16 v[72:75], v[72:75], v[96:99], v[52:55]
	v_mfma_f32_16x16x32_bf16 v[68:71], v[68:71], v[96:99], v[56:59]
	v_mfma_f32_16x16x32_bf16 v[64:67], v[64:67], v[96:99], v[60:63]
	ds_read_b128 v[32:35], v241 offset:64
	ds_read_b128 v[96:99], v241 offset:2368
	ds_read_b128 v[100:103], v181 offset:18496
	ds_read_b128 v[104:107], v181 offset:20800
	ds_read_b128 v[108:111], v181 offset:23104
	ds_read_b128 v[112:115], v181 offset:25408
	ds_read_b128 v[116:119], v181 offset:27712
	ds_read_b128 v[120:123], v181 offset:30016
	ds_read_b128 v[158:161], v181 offset:32320
	ds_read_b128 v[162:165], v181 offset:34624
	s_waitcnt lgkmcnt(5)
	v_mfma_f32_16x16x32_bf16 v[52:55], v[108:111], v[32:35], v[8:11]
	s_waitcnt lgkmcnt(4)
	v_mfma_f32_16x16x32_bf16 v[48:51], v[112:115], v[32:35], v[12:15]
	s_waitcnt lgkmcnt(2)
	v_mfma_f32_16x16x32_bf16 v[40:43], v[120:123], v[32:35], v[20:23]
	v_mfma_f32_16x16x32_bf16 v[20:23], v[108:111], v[96:99], v[84:87]
	v_add_u32_e32 v108, s10, v182
	v_mfma_f32_16x16x32_bf16 v[12:15], v[116:119], v[96:99], v[76:79]
	s_nop 2
	v_mov_b64_e32 v[76:77], s[0:1]
	v_mfma_f32_16x16x32_bf16 v[44:47], v[116:119], v[32:35], v[16:19]
	v_mfma_f32_16x16x32_bf16 v[16:19], v[112:115], v[96:99], v[80:83]
	s_nop 2
	v_mad_i64_i32 v[82:83], s[0:1], v108, s96, v[76:77]
	v_readlane_b32 s0, v252, 43
	v_readlane_b32 s1, v252, 44
	v_mfma_f32_16x16x32_bf16 v[60:63], v[100:103], v[32:35], v[0:3]
	s_nop 0
	v_mov_b64_e32 v[78:79], s[0:1]
	v_mfma_f32_16x16x32_bf16 v[56:59], v[104:107], v[32:35], v[4:7]
	s_waitcnt lgkmcnt(1)
	v_mfma_f32_16x16x32_bf16 v[36:39], v[158:161], v[32:35], v[24:27]
	s_nop 2
	v_mov_b32_e32 v113, v61
	v_mov_b32_e32 v111, v60
	s_waitcnt lgkmcnt(0)
	v_mfma_f32_16x16x32_bf16 v[32:35], v[162:165], v[32:35], v[28:31]
	v_mfma_f32_16x16x32_bf16 v[28:31], v[100:103], v[96:99], v[92:95]
	v_mad_i64_i32 v[100:101], s[0:1], v108, s97, v[78:79]
	v_readlane_b32 s0, v252, 21
	v_mfma_f32_16x16x32_bf16 v[8:11], v[120:123], v[96:99], v[72:75]
	v_readlane_b32 s4, v252, 25
	v_readlane_b32 s5, v252, 26
	s_nop 2
	v_mov_b32_e32 v112, v29
	v_or_b32_e32 v74, s78, v185
	v_ashrrev_i32_e32 v75, 31, v74
	v_lshl_add_u64 v[72:73], v[74:75], 2, s[4:5]
	v_lshlrev_b64 v[74:75], 1, v[74:75]
	v_lshl_add_u64 v[84:85], v[82:83], 0, v[74:75]
	v_mfma_f32_16x16x32_bf16 v[24:27], v[104:107], v[96:99], v[88:91]
	v_mov_b32_e32 v110, v28
	v_pk_mul_f32 v[112:113], v[112:113], v[112:113]
	v_pk_mul_f32 v[94:95], v[36:37], v[36:37]
	v_mfma_f32_16x16x32_bf16 v[4:7], v[158:161], v[96:99], v[68:71]
	v_fma_f32 v110, v110, v110, v112
	v_fma_f32 v111, v111, v111, v113
	v_mov_b32_e32 v112, v30
	v_mov_b32_e32 v113, v62
	v_mfma_f32_16x16x32_bf16 v[0:3], v[162:165], v[96:99], v[64:67]
	s_nop 2
	global_load_dwordx4 v[64:67], v[72:73], off offset:16
	global_load_dwordx4 v[68:71], v[72:73], off
	global_load_dwordx4 v[96:99], v[84:85], off
	global_load_dwordx4 v[104:107], v[84:85], off offset:64
	v_pk_fma_f32 v[110:111], v[112:113], v[112:113], v[110:111]
	v_mov_b32_e32 v112, v31
	v_mov_b32_e32 v113, v63
	v_pk_fma_f32 v[110:111], v[112:113], v[112:113], v[110:111]
	v_mov_b32_e32 v112, v24
	v_mov_b32_e32 v113, v56
	v_pk_fma_f32 v[110:111], v[112:113], v[112:113], v[110:111]
	v_mov_b32_e32 v112, v25
	v_mov_b32_e32 v113, v57
	v_pk_fma_f32 v[110:111], v[112:113], v[112:113], v[110:111]
	v_mov_b32_e32 v112, v26
	v_mov_b32_e32 v113, v58
	v_pk_fma_f32 v[110:111], v[112:113], v[112:113], v[110:111]
	v_mov_b32_e32 v112, v27
	v_mov_b32_e32 v113, v59
	v_pk_fma_f32 v[110:111], v[112:113], v[112:113], v[110:111]
	v_mov_b32_e32 v112, v20
	v_mov_b32_e32 v113, v52
	v_pk_fma_f32 v[110:111], v[112:113], v[112:113], v[110:111]
	v_mov_b32_e32 v112, v21
	v_mov_b32_e32 v113, v53
	v_pk_fma_f32 v[110:111], v[112:113], v[112:113], v[110:111]
	v_mov_b32_e32 v112, v22
	v_mov_b32_e32 v113, v54
	v_pk_fma_f32 v[110:111], v[112:113], v[112:113], v[110:111]
	v_mov_b32_e32 v112, v23
	v_mov_b32_e32 v113, v55
	v_pk_fma_f32 v[110:111], v[112:113], v[112:113], v[110:111]
	v_mov_b32_e32 v112, v16
	v_mov_b32_e32 v113, v48
	v_pk_fma_f32 v[110:111], v[112:113], v[112:113], v[110:111]
	v_mov_b32_e32 v112, v17
	v_mov_b32_e32 v113, v49
	v_pk_fma_f32 v[110:111], v[112:113], v[112:113], v[110:111]
	v_mov_b32_e32 v112, v18
	v_mov_b32_e32 v113, v50
	v_pk_fma_f32 v[110:111], v[112:113], v[112:113], v[110:111]
	v_mov_b32_e32 v112, v19
	v_mov_b32_e32 v113, v51
	v_pk_fma_f32 v[110:111], v[112:113], v[112:113], v[110:111]
	v_mov_b32_e32 v112, v12
	v_mov_b32_e32 v113, v44
	v_pk_fma_f32 v[110:111], v[112:113], v[112:113], v[110:111]
	v_mov_b32_e32 v112, v13
	v_mov_b32_e32 v113, v45
	v_pk_fma_f32 v[110:111], v[112:113], v[112:113], v[110:111]
	v_mov_b32_e32 v112, v14
	v_mov_b32_e32 v113, v46
	v_pk_fma_f32 v[110:111], v[112:113], v[112:113], v[110:111]
	v_mov_b32_e32 v112, v15
	v_mov_b32_e32 v113, v47
	v_pk_fma_f32 v[110:111], v[112:113], v[112:113], v[110:111]
	v_mov_b32_e32 v112, v8
	v_mov_b32_e32 v113, v40
	v_pk_fma_f32 v[110:111], v[112:113], v[112:113], v[110:111]
	v_mov_b32_e32 v112, v9
	v_mov_b32_e32 v113, v41
	v_pk_fma_f32 v[110:111], v[112:113], v[112:113], v[110:111]
	v_mov_b32_e32 v112, v10
	v_mov_b32_e32 v113, v42
	v_pk_mul_f32 v[116:117], v[4:5], v[4:5]
	v_pk_fma_f32 v[110:111], v[112:113], v[112:113], v[110:111]
	v_mov_b32_e32 v112, v11
	v_mov_b32_e32 v113, v43
	v_pk_fma_f32 v[110:111], v[112:113], v[112:113], v[110:111]
	v_mov_b32_e32 v112, v116
	v_mov_b32_e32 v113, v94
	v_pk_mul_f32 v[90:91], v[38:39], v[38:39]
	v_pk_mul_f32 v[114:115], v[6:7], v[6:7]
	v_pk_add_f32 v[110:111], v[112:113], v[110:111]
	v_mov_b32_e32 v94, v117
	v_pk_add_f32 v[94:95], v[94:95], v[110:111]
	v_mov_b32_e32 v110, v114
	v_mov_b32_e32 v111, v90
	v_pk_mul_f32 v[86:87], v[32:33], v[32:33]
	v_pk_mul_f32 v[118:119], v[0:1], v[0:1]
	v_pk_add_f32 v[94:95], v[110:111], v[94:95]
	v_mov_b32_e32 v90, v115
	s_waitcnt vmcnt(1)
	v_lshlrev_b32_e32 v82, 16, v96
	v_mul_f32_e32 v82, 0xbfb8aa3b, v82
	v_exp_f32_e32 v82, v82
	v_pk_add_f32 v[90:91], v[90:91], v[94:95]
	v_mov_b32_e32 v94, v118
	v_mov_b32_e32 v95, v86
	v_add_f32_e32 v82, 1.0, v82
	v_rcp_f32_e32 v88, v82
	v_and_b32_e32 v82, 0xffff0000, v96
	v_mul_f32_e32 v82, 0xbfb8aa3b, v82
	v_exp_f32_e32 v82, v82
	v_pk_mul_f32 v[80:81], v[34:35], v[34:35]
	v_pk_mul_f32 v[112:113], v[2:3], v[2:3]
	v_pk_add_f32 v[90:91], v[94:95], v[90:91]
	v_add_f32_e32 v82, 1.0, v82
	v_rcp_f32_e32 v89, v82
	v_lshlrev_b32_e32 v82, 16, v97
	v_mul_f32_e32 v82, 0xbfb8aa3b, v82
	v_exp_f32_e32 v82, v82
	v_mov_b32_e32 v86, v119
	v_pk_add_f32 v[86:87], v[86:87], v[90:91]
	v_mov_b32_e32 v90, v112
	v_add_f32_e32 v82, 1.0, v82
	v_rcp_f32_e32 v92, v82
	v_and_b32_e32 v82, 0xffff0000, v97
	v_mul_f32_e32 v82, 0xbfb8aa3b, v82
	v_exp_f32_e32 v82, v82
	v_mov_b32_e32 v91, v80
	v_pk_add_f32 v[86:87], v[90:91], v[86:87]
	v_mov_b32_e32 v80, v113
	v_add_f32_e32 v82, 1.0, v82
	v_rcp_f32_e32 v93, v82
	v_lshlrev_b32_e32 v82, 16, v98
	v_mul_f32_e32 v82, 0xbfb8aa3b, v82
	v_exp_f32_e32 v82, v82
	v_pk_add_f32 v[80:81], v[80:81], v[86:87]
	ds_bpermute_b32 v87, v183, v81
	ds_bpermute_b32 v86, v183, v80
	v_add_f32_e32 v82, 1.0, v82
	v_rcp_f32_e32 v96, v82
	v_and_b32_e32 v82, 0xffff0000, v98
	v_mul_f32_e32 v82, 0xbfb8aa3b, v82
	v_exp_f32_e32 v82, v82
	s_waitcnt lgkmcnt(0)
	v_pk_add_f32 v[80:81], v[80:81], v[86:87]
	ds_bpermute_b32 v87, v184, v81
	ds_bpermute_b32 v86, v184, v80
	v_add_f32_e32 v82, 1.0, v82
	v_rcp_f32_e32 v97, v82
	v_lshlrev_b32_e32 v82, 16, v99
	v_mul_f32_e32 v82, 0xbfb8aa3b, v82
	v_exp_f32_e32 v82, v82
	v_readlane_b32 s1, v252, 22
	s_waitcnt lgkmcnt(0)
	v_pk_add_f32 v[80:81], v[80:81], v[86:87]
	s_brev_b32 s0, 60
	v_pk_fma_f32 v[80:81], v[80:81], s[0:1], v[156:157] op_sel_hi:[1,0,0]
	s_mov_b32 s0, 0x800000
	v_mul_f32_e32 v86, 0x4b800000, v81
	v_cmp_gt_f32_e32 vcc, s0, v81
	v_add_f32_e32 v82, 1.0, v82
	v_rcp_f32_e32 v98, v82
	v_cndmask_b32_e32 v81, v81, v86, vcc
	v_and_b32_e32 v82, 0xffff0000, v99
	v_rsq_f32_e32 v81, v81
	v_mul_f32_e32 v82, 0xbfb8aa3b, v82
	v_exp_f32_e32 v82, v82
	s_waitcnt vmcnt(0)
	v_lshlrev_b32_e32 v102, 16, v105
	v_mul_f32_e32 v86, 0x45800000, v81
	v_cndmask_b32_e32 v86, v81, v86, vcc
	v_add_f32_e32 v82, 1.0, v82
	v_pk_mul_f32 v[60:61], v[60:61], v[86:87] op_sel_hi:[1,0]
	v_pk_mul_f32 v[62:63], v[62:63], v[86:87] op_sel_hi:[1,0]
	v_pk_mul_f32 v[56:57], v[56:57], v[86:87] op_sel_hi:[1,0]
	v_rcp_f32_e32 v99, v82
	v_pk_mul_f32 v[60:61], v[68:69], v[60:61]
	v_pk_mul_f32 v[62:63], v[70:71], v[62:63]
	v_pk_mul_f32 v[56:57], v[64:65], v[56:57]
	v_pk_mul_f32 v[60:61], v[88:89], v[60:61]
	v_pk_mul_f32 v[62:63], v[92:93], v[62:63]
	v_pk_mul_f32 v[56:57], v[96:97], v[56:57]
	v_cvt_pk_bf16_f32 v60, v60, v61
	v_cvt_pk_bf16_f32 v61, v62, v63
	v_cvt_pk_bf16_f32 v62, v56, v57
	v_pk_mul_f32 v[56:57], v[58:59], v[86:87] op_sel_hi:[1,0]
	v_lshl_add_u64 v[82:83], v[100:101], 0, v[74:75]
	v_pk_mul_f32 v[56:57], v[66:67], v[56:57]
	v_lshlrev_b32_e32 v100, 16, v104
	v_pk_mul_f32 v[56:57], v[98:99], v[56:57]
	v_and_b32_e32 v101, 0xffff0000, v104
	v_cvt_pk_bf16_f32 v63, v56, v57
	global_store_dwordx4 v[82:83], v[60:63], off
	global_load_dwordx4 v[56:59], v[72:73], off offset:144
	s_nop 0
	global_load_dwordx4 v[60:63], v[72:73], off offset:128
	v_and_b32_e32 v103, 0xffff0000, v105
	v_lshlrev_b32_e32 v104, 16, v106
	v_and_b32_e32 v105, 0xffff0000, v106
	v_mul_f32_e32 v100, 0xbfb8aa3b, v100
	v_mul_f32_e32 v101, 0xbfb8aa3b, v101
	v_mul_f32_e32 v102, 0xbfb8aa3b, v102
	v_mul_f32_e32 v103, 0xbfb8aa3b, v103
	v_mul_f32_e32 v104, 0xbfb8aa3b, v104
	v_mul_f32_e32 v105, 0xbfb8aa3b, v105
	v_exp_f32_e32 v100, v100
	v_exp_f32_e32 v101, v101
	v_exp_f32_e32 v102, v102
	v_exp_f32_e32 v103, v103
	v_exp_f32_e32 v104, v104
	v_exp_f32_e32 v105, v105
	v_lshlrev_b32_e32 v106, 16, v107
	v_and_b32_e32 v107, 0xffff0000, v107
	v_mul_f32_e32 v106, 0xbfb8aa3b, v106
	v_mul_f32_e32 v107, 0xbfb8aa3b, v107
	v_exp_f32_e32 v106, v106
	v_exp_f32_e32 v107, v107
	v_add_f32_e32 v100, 1.0, v100
	v_add_f32_e32 v101, 1.0, v101
	v_add_f32_e32 v102, 1.0, v102
	v_add_f32_e32 v103, 1.0, v103
	v_add_f32_e32 v104, 1.0, v104
	v_add_f32_e32 v105, 1.0, v105
	v_rcp_f32_e32 v100, v100
	v_rcp_f32_e32 v101, v101
	v_rcp_f32_e32 v102, v102
	v_rcp_f32_e32 v103, v103
	v_rcp_f32_e32 v104, v104
	v_rcp_f32_e32 v105, v105
	v_add_f32_e32 v106, 1.0, v106
	v_add_f32_e32 v107, 1.0, v107
	v_pk_mul_f32 v[52:53], v[52:53], v[86:87] op_sel_hi:[1,0]
	v_pk_mul_f32 v[54:55], v[54:55], v[86:87] op_sel_hi:[1,0]
	v_pk_mul_f32 v[48:49], v[48:49], v[86:87] op_sel_hi:[1,0]
	v_rcp_f32_e32 v106, v106
	v_rcp_f32_e32 v107, v107
	v_pk_mul_f32 v[44:45], v[44:45], v[86:87] op_sel_hi:[1,0]
	v_pk_mul_f32 v[46:47], v[46:47], v[86:87] op_sel_hi:[1,0]
	v_pk_mul_f32 v[40:41], v[40:41], v[86:87] op_sel_hi:[1,0]
	v_pk_mul_f32 v[42:43], v[42:43], v[86:87] op_sel_hi:[1,0]
	v_pk_mul_f32 v[36:37], v[36:37], v[86:87] op_sel_hi:[1,0]
	v_pk_mul_f32 v[38:39], v[38:39], v[86:87] op_sel_hi:[1,0]
	v_pk_mul_f32 v[32:33], v[32:33], v[86:87] op_sel_hi:[1,0]
	v_pk_mul_f32 v[34:35], v[34:35], v[86:87] op_sel_hi:[1,0]
	v_cmp_gt_f32_e64 s[78:79], s0, v80
	v_or_b32_e32 v108, 16, v108
	v_readlane_b32 s2, v252, 23
	v_readlane_b32 s3, v252, 24
	v_readlane_b32 s6, v252, 27
	v_readlane_b32 s7, v252, 28
	v_readlane_b32 s8, v252, 29
	v_readlane_b32 s9, v252, 30
	v_readlane_b32 s10, v252, 31
	v_readlane_b32 s11, v252, 32
	v_readlane_b32 s12, v252, 33
	v_readlane_b32 s13, v252, 34
	v_readlane_b32 s14, v252, 35
	v_readlane_b32 s15, v252, 36
	s_waitcnt vmcnt(1)
	v_pk_mul_f32 v[48:49], v[56:57], v[48:49]
	s_waitcnt vmcnt(0)
	v_pk_mul_f32 v[52:53], v[60:61], v[52:53]
	v_pk_mul_f32 v[54:55], v[62:63], v[54:55]
	v_pk_mul_f32 v[52:53], v[100:101], v[52:53]
	v_pk_mul_f32 v[54:55], v[102:103], v[54:55]
	v_pk_mul_f32 v[48:49], v[104:105], v[48:49]
	v_cvt_pk_bf16_f32 v52, v52, v53
	v_cvt_pk_bf16_f32 v53, v54, v55
	v_cvt_pk_bf16_f32 v54, v48, v49
	v_pk_mul_f32 v[48:49], v[50:51], v[86:87] op_sel_hi:[1,0]
	s_nop 0
	v_pk_mul_f32 v[48:49], v[58:59], v[48:49]
	s_nop 0
	v_pk_mul_f32 v[48:49], v[106:107], v[48:49]
	s_nop 0
	v_cvt_pk_bf16_f32 v55, v48, v49
	global_store_dwordx4 v[82:83], v[52:55], off offset:64
	global_load_dwordx4 v[48:51], v[72:73], off offset:272
	s_nop 0
	global_load_dwordx4 v[52:55], v[72:73], off offset:256
	global_load_dwordx4 v[56:59], v[84:85], off offset:128
	s_waitcnt vmcnt(2)
	v_pk_mul_f32 v[40:41], v[48:49], v[40:41]
	s_waitcnt vmcnt(1)
	v_pk_mul_f32 v[44:45], v[52:53], v[44:45]
	s_waitcnt vmcnt(0)
	v_lshlrev_b32_e32 v60, 16, v56
	v_and_b32_e32 v56, 0xffff0000, v56
	v_mul_f32_e32 v60, 0xbfb8aa3b, v60
	v_mul_f32_e32 v56, 0xbfb8aa3b, v56
	v_exp_f32_e32 v60, v60
	v_exp_f32_e32 v56, v56
	v_pk_mul_f32 v[46:47], v[54:55], v[46:47]
	v_pk_mul_f32 v[42:43], v[50:51], v[42:43]
	v_add_f32_e32 v60, 1.0, v60
	v_add_f32_e32 v56, 1.0, v56
	v_rcp_f32_e32 v60, v60
	v_rcp_f32_e32 v61, v56
	s_nop 0
	v_pk_mul_f32 v[44:45], v[44:45], v[60:61]
	s_nop 0
	v_cvt_pk_bf16_f32 v44, v44, v45
	v_lshlrev_b32_e32 v45, 16, v57
	v_mul_f32_e32 v45, 0xbfb8aa3b, v45
	v_exp_f32_e32 v45, v45
	s_nop 0
	v_add_f32_e32 v45, 1.0, v45
	v_rcp_f32_e32 v52, v45
	v_and_b32_e32 v45, 0xffff0000, v57
	v_mul_f32_e32 v45, 0xbfb8aa3b, v45
	v_exp_f32_e32 v45, v45
	s_nop 0
	v_add_f32_e32 v45, 1.0, v45
	v_rcp_f32_e32 v53, v45
	s_nop 0
	v_pk_mul_f32 v[46:47], v[46:47], v[52:53]
	s_nop 0
	v_cvt_pk_bf16_f32 v45, v46, v47
	v_lshlrev_b32_e32 v46, 16, v58
	v_and_b32_e32 v47, 0xffff0000, v58
	v_mul_f32_e32 v46, 0xbfb8aa3b, v46
	v_mul_f32_e32 v47, 0xbfb8aa3b, v47
	v_exp_f32_e32 v46, v46
	v_exp_f32_e32 v47, v47
	v_add_f32_e32 v46, 1.0, v46
	v_add_f32_e32 v47, 1.0, v47
	v_rcp_f32_e32 v46, v46
	v_rcp_f32_e32 v47, v47
	s_nop 0
	v_pk_mul_f32 v[40:41], v[40:41], v[46:47]
	s_nop 0
	v_cvt_pk_bf16_f32 v46, v40, v41
	v_lshlrev_b32_e32 v40, 16, v59
	v_and_b32_e32 v41, 0xffff0000, v59
	v_mul_f32_e32 v40, 0xbfb8aa3b, v40
	v_mul_f32_e32 v41, 0xbfb8aa3b, v41
	v_exp_f32_e32 v40, v40
	v_exp_f32_e32 v41, v41
	v_add_f32_e32 v40, 1.0, v40
	v_add_f32_e32 v41, 1.0, v41
	v_rcp_f32_e32 v40, v40
	v_rcp_f32_e32 v41, v41
	s_nop 0
	v_pk_mul_f32 v[40:41], v[42:43], v[40:41]
	s_nop 0
	v_cvt_pk_bf16_f32 v47, v40, v41
	global_store_dwordx4 v[82:83], v[44:47], off offset:128
	global_load_dwordx4 v[40:43], v[72:73], off offset:400
	s_nop 0
	global_load_dwordx4 v[44:47], v[72:73], off offset:384
	global_load_dwordx4 v[48:51], v[84:85], off offset:192
	s_waitcnt vmcnt(2)
	v_pk_mul_f32 v[32:33], v[32:33], v[40:41]
	s_waitcnt vmcnt(1)
	v_pk_mul_f32 v[36:37], v[36:37], v[44:45]
	s_waitcnt vmcnt(0)
	v_lshlrev_b32_e32 v52, 16, v48
	v_and_b32_e32 v48, 0xffff0000, v48
	v_mul_f32_e32 v52, 0xbfb8aa3b, v52
	v_mul_f32_e32 v48, 0xbfb8aa3b, v48
	v_exp_f32_e32 v52, v52
	v_exp_f32_e32 v48, v48
	v_pk_mul_f32 v[38:39], v[38:39], v[46:47]
	v_pk_mul_f32 v[34:35], v[34:35], v[42:43]
	v_add_f32_e32 v52, 1.0, v52
	v_add_f32_e32 v48, 1.0, v48
	v_rcp_f32_e32 v52, v52
	v_rcp_f32_e32 v53, v48
	s_nop 0
	v_pk_mul_f32 v[36:37], v[36:37], v[52:53]
	s_nop 0
	v_cvt_pk_bf16_f32 v36, v36, v37
	v_lshlrev_b32_e32 v37, 16, v49
	v_mul_f32_e32 v37, 0xbfb8aa3b, v37
	v_exp_f32_e32 v37, v37
	s_nop 0
	v_add_f32_e32 v37, 1.0, v37
	v_rcp_f32_e32 v44, v37
	v_and_b32_e32 v37, 0xffff0000, v49
	v_mul_f32_e32 v37, 0xbfb8aa3b, v37
	v_exp_f32_e32 v37, v37
	s_nop 0
	v_add_f32_e32 v37, 1.0, v37
	v_rcp_f32_e32 v45, v37
	s_nop 0
	v_pk_mul_f32 v[38:39], v[38:39], v[44:45]
	s_nop 0
	v_cvt_pk_bf16_f32 v37, v38, v39
	v_lshlrev_b32_e32 v38, 16, v50
	v_and_b32_e32 v39, 0xffff0000, v50
	v_mul_f32_e32 v38, 0xbfb8aa3b, v38
	v_mul_f32_e32 v39, 0xbfb8aa3b, v39
	v_exp_f32_e32 v38, v38
	v_exp_f32_e32 v39, v39
	v_add_f32_e32 v38, 1.0, v38
	v_add_f32_e32 v39, 1.0, v39
	v_rcp_f32_e32 v38, v38
	v_rcp_f32_e32 v39, v39
	s_nop 0
	v_pk_mul_f32 v[32:33], v[32:33], v[38:39]
	s_nop 0
	v_cvt_pk_bf16_f32 v38, v32, v33
	v_lshlrev_b32_e32 v32, 16, v51
	v_and_b32_e32 v33, 0xffff0000, v51
	v_mul_f32_e32 v32, 0xbfb8aa3b, v32
	v_mul_f32_e32 v33, 0xbfb8aa3b, v33
	v_exp_f32_e32 v32, v32
	v_exp_f32_e32 v33, v33
	v_mad_i64_i32 v[50:51], s[0:1], v108, s97, v[78:79]
	v_add_f32_e32 v32, 1.0, v32
	v_add_f32_e32 v33, 1.0, v33
	v_rcp_f32_e32 v32, v32
	v_rcp_f32_e32 v33, v33
	s_nop 0
	v_pk_mul_f32 v[32:33], v[34:35], v[32:33]
	s_nop 0
	v_cvt_pk_bf16_f32 v39, v32, v33
	v_mul_f32_e32 v32, 0x4b800000, v80
	v_cndmask_b32_e64 v32, v80, v32, s[78:79]
	v_rsq_f32_e32 v32, v32
	global_store_dwordx4 v[82:83], v[36:39], off offset:192
	v_mul_f32_e32 v33, 0x45800000, v32
	s_nop 0
	v_mad_i64_i32 v[38:39], s[0:1], v108, s96, v[76:77]
	v_lshl_add_u64 v[40:41], v[38:39], 0, v[74:75]
	v_cndmask_b32_e64 v36, v32, v33, s[78:79]
	global_load_dwordx4 v[32:35], v[72:73], off offset:16
	global_load_dwordx4 v[42:45], v[72:73], off
	global_load_dwordx4 v[46:49], v[40:41], off
	s_mov_b64 s[78:79], s[18:19]
	s_waitcnt vmcnt(0)
	v_lshlrev_b32_e32 v37, 16, v46
	v_mul_f32_e32 v37, 0xbfb8aa3b, v37
	v_exp_f32_e32 v37, v37
	s_nop 0
	v_add_f32_e32 v37, 1.0, v37
	v_rcp_f32_e32 v38, v37
	v_and_b32_e32 v37, 0xffff0000, v46
	v_mul_f32_e32 v37, 0xbfb8aa3b, v37
	v_exp_f32_e32 v37, v37
	s_nop 0
	v_add_f32_e32 v37, 1.0, v37
	v_rcp_f32_e32 v39, v37
	v_pk_mul_f32 v[28:29], v[28:29], v[36:37] op_sel_hi:[1,0]
	v_pk_mul_f32 v[30:31], v[30:31], v[36:37] op_sel_hi:[1,0]
	v_pk_mul_f32 v[28:29], v[42:43], v[28:29]
	v_pk_mul_f32 v[30:31], v[44:45], v[30:31]
	v_pk_mul_f32 v[28:29], v[38:39], v[28:29]
	v_pk_mul_f32 v[24:25], v[24:25], v[36:37] op_sel_hi:[1,0]
	v_cvt_pk_bf16_f32 v28, v28, v29
	v_lshlrev_b32_e32 v29, 16, v47
	v_mul_f32_e32 v29, 0xbfb8aa3b, v29
	v_exp_f32_e32 v29, v29
	v_pk_mul_f32 v[24:25], v[32:33], v[24:25]
	v_pk_mul_f32 v[26:27], v[26:27], v[36:37] op_sel_hi:[1,0]
	v_add_f32_e32 v29, 1.0, v29
	v_rcp_f32_e32 v38, v29
	v_and_b32_e32 v29, 0xffff0000, v47
	v_mul_f32_e32 v29, 0xbfb8aa3b, v29
	v_exp_f32_e32 v29, v29
	v_pk_mul_f32 v[26:27], v[34:35], v[26:27]
	v_add_f32_e32 v29, 1.0, v29
	v_rcp_f32_e32 v39, v29
	s_nop 0
	v_pk_mul_f32 v[30:31], v[38:39], v[30:31]
	s_nop 0
	v_cvt_pk_bf16_f32 v29, v30, v31
	v_lshlrev_b32_e32 v30, 16, v48
	v_and_b32_e32 v31, 0xffff0000, v48
	v_mul_f32_e32 v30, 0xbfb8aa3b, v30
	v_mul_f32_e32 v31, 0xbfb8aa3b, v31
	v_exp_f32_e32 v30, v30
	v_exp_f32_e32 v31, v31
	v_lshl_add_u64 v[38:39], v[50:51], 0, v[74:75]
	v_add_f32_e32 v30, 1.0, v30
	v_add_f32_e32 v31, 1.0, v31
	v_rcp_f32_e32 v30, v30
	v_rcp_f32_e32 v31, v31
	s_nop 0
	v_pk_mul_f32 v[24:25], v[24:25], v[30:31]
	s_nop 0
	v_cvt_pk_bf16_f32 v30, v24, v25
	v_lshlrev_b32_e32 v24, 16, v49
	v_and_b32_e32 v25, 0xffff0000, v49
	v_mul_f32_e32 v24, 0xbfb8aa3b, v24
	v_mul_f32_e32 v25, 0xbfb8aa3b, v25
	v_exp_f32_e32 v24, v24
	v_exp_f32_e32 v25, v25
	v_add_f32_e32 v24, 1.0, v24
	v_add_f32_e32 v25, 1.0, v25
	v_rcp_f32_e32 v24, v24
	v_rcp_f32_e32 v25, v25
	s_nop 0
	v_pk_mul_f32 v[24:25], v[26:27], v[24:25]
	s_nop 0
	v_cvt_pk_bf16_f32 v31, v24, v25
	global_store_dwordx4 v[38:39], v[28:31], off
	global_load_dwordx4 v[24:27], v[72:73], off offset:144
	s_nop 0
	global_load_dwordx4 v[28:31], v[72:73], off offset:128
	global_load_dwordx4 v[32:35], v[40:41], off offset:64
	s_waitcnt vmcnt(0)
	v_lshlrev_b32_e32 v37, 16, v32
	v_and_b32_e32 v32, 0xffff0000, v32
	v_mul_f32_e32 v37, 0xbfb8aa3b, v37
	v_mul_f32_e32 v32, 0xbfb8aa3b, v32
	v_exp_f32_e32 v37, v37
	v_exp_f32_e32 v32, v32
	v_add_f32_e32 v37, 1.0, v37
	v_add_f32_e32 v32, 1.0, v32
	v_rcp_f32_e32 v42, v37
	v_rcp_f32_e32 v43, v32
	v_pk_mul_f32 v[20:21], v[20:21], v[36:37] op_sel_hi:[1,0]
	v_pk_mul_f32 v[22:23], v[22:23], v[36:37] op_sel_hi:[1,0]
	v_pk_mul_f32 v[20:21], v[20:21], v[28:29]
	v_pk_mul_f32 v[22:23], v[22:23], v[30:31]
	v_pk_mul_f32 v[20:21], v[20:21], v[42:43]
	v_pk_mul_f32 v[16:17], v[16:17], v[36:37] op_sel_hi:[1,0]
	v_cvt_pk_bf16_f32 v20, v20, v21
	v_lshlrev_b32_e32 v21, 16, v33
	v_mul_f32_e32 v21, 0xbfb8aa3b, v21
	v_exp_f32_e32 v21, v21
	v_pk_mul_f32 v[16:17], v[16:17], v[24:25]
	v_pk_mul_f32 v[18:19], v[18:19], v[36:37] op_sel_hi:[1,0]
	v_pk_mul_f32 v[12:13], v[12:13], v[36:37] op_sel_hi:[1,0]
	v_add_f32_e32 v21, 1.0, v21
	v_rcp_f32_e32 v28, v21
	v_and_b32_e32 v21, 0xffff0000, v33
	v_mul_f32_e32 v21, 0xbfb8aa3b, v21
	v_exp_f32_e32 v21, v21
	v_pk_mul_f32 v[18:19], v[18:19], v[26:27]
	v_pk_mul_f32 v[14:15], v[14:15], v[36:37] op_sel_hi:[1,0]
	v_pk_mul_f32 v[8:9], v[8:9], v[36:37] op_sel_hi:[1,0]
	v_add_f32_e32 v21, 1.0, v21
	v_rcp_f32_e32 v29, v21
	v_pk_mul_f32 v[10:11], v[10:11], v[36:37] op_sel_hi:[1,0]
	v_pk_mul_f32 v[4:5], v[4:5], v[36:37] op_sel_hi:[1,0]
	v_pk_mul_f32 v[6:7], v[6:7], v[36:37] op_sel_hi:[1,0]
	v_pk_mul_f32 v[22:23], v[22:23], v[28:29]
	v_pk_mul_f32 v[0:1], v[0:1], v[36:37] op_sel_hi:[1,0]
	v_cvt_pk_bf16_f32 v21, v22, v23
	v_lshlrev_b32_e32 v22, 16, v34
	v_and_b32_e32 v23, 0xffff0000, v34
	v_mul_f32_e32 v22, 0xbfb8aa3b, v22
	v_mul_f32_e32 v23, 0xbfb8aa3b, v23
	v_exp_f32_e32 v22, v22
	v_exp_f32_e32 v23, v23
	v_pk_mul_f32 v[2:3], v[2:3], v[36:37] op_sel_hi:[1,0]
	v_add_f32_e32 v22, 1.0, v22
	v_add_f32_e32 v23, 1.0, v23
	v_rcp_f32_e32 v22, v22
	v_rcp_f32_e32 v23, v23
	s_nop 0
	v_pk_mul_f32 v[16:17], v[16:17], v[22:23]
	s_nop 0
	v_cvt_pk_bf16_f32 v22, v16, v17
	v_lshlrev_b32_e32 v16, 16, v35
	v_and_b32_e32 v17, 0xffff0000, v35
	v_mul_f32_e32 v16, 0xbfb8aa3b, v16
	v_mul_f32_e32 v17, 0xbfb8aa3b, v17
	v_exp_f32_e32 v16, v16
	v_exp_f32_e32 v17, v17
	v_add_f32_e32 v16, 1.0, v16
	v_add_f32_e32 v17, 1.0, v17
	v_rcp_f32_e32 v16, v16
	v_rcp_f32_e32 v17, v17
	s_nop 0
	v_pk_mul_f32 v[16:17], v[18:19], v[16:17]
	s_nop 0
	v_cvt_pk_bf16_f32 v23, v16, v17
	global_store_dwordx4 v[38:39], v[20:23], off offset:64
	global_load_dwordx4 v[16:19], v[72:73], off offset:272
	s_nop 0
	global_load_dwordx4 v[20:23], v[72:73], off offset:256
	global_load_dwordx4 v[24:27], v[40:41], off offset:128
	s_waitcnt vmcnt(2)
	v_pk_mul_f32 v[8:9], v[8:9], v[16:17]
	s_waitcnt vmcnt(1)
	v_pk_mul_f32 v[12:13], v[12:13], v[20:21]
	s_waitcnt vmcnt(0)
	v_lshlrev_b32_e32 v28, 16, v24
	v_and_b32_e32 v24, 0xffff0000, v24
	v_mul_f32_e32 v28, 0xbfb8aa3b, v28
	v_mul_f32_e32 v24, 0xbfb8aa3b, v24
	v_exp_f32_e32 v28, v28
	v_exp_f32_e32 v24, v24
	v_pk_mul_f32 v[14:15], v[14:15], v[22:23]
	v_pk_mul_f32 v[10:11], v[10:11], v[18:19]
	v_add_f32_e32 v28, 1.0, v28
	v_add_f32_e32 v24, 1.0, v24
	v_rcp_f32_e32 v28, v28
	v_rcp_f32_e32 v29, v24
	s_nop 0
	v_pk_mul_f32 v[12:13], v[12:13], v[28:29]
	s_nop 0
	v_cvt_pk_bf16_f32 v12, v12, v13
	v_lshlrev_b32_e32 v13, 16, v25
	v_mul_f32_e32 v13, 0xbfb8aa3b, v13
	v_exp_f32_e32 v13, v13
	s_nop 0
	v_add_f32_e32 v13, 1.0, v13
	v_rcp_f32_e32 v20, v13
	v_and_b32_e32 v13, 0xffff0000, v25
	v_mul_f32_e32 v13, 0xbfb8aa3b, v13
	v_exp_f32_e32 v13, v13
	s_nop 0
	v_add_f32_e32 v13, 1.0, v13
	v_rcp_f32_e32 v21, v13
	s_nop 0
	v_pk_mul_f32 v[14:15], v[14:15], v[20:21]
	s_nop 0
	v_cvt_pk_bf16_f32 v13, v14, v15
	v_lshlrev_b32_e32 v14, 16, v26
	v_and_b32_e32 v15, 0xffff0000, v26
	v_mul_f32_e32 v14, 0xbfb8aa3b, v14
	v_mul_f32_e32 v15, 0xbfb8aa3b, v15
	v_exp_f32_e32 v14, v14
	v_exp_f32_e32 v15, v15
	v_add_f32_e32 v14, 1.0, v14
	v_add_f32_e32 v15, 1.0, v15
	v_rcp_f32_e32 v14, v14
	v_rcp_f32_e32 v15, v15
	s_nop 0
	v_pk_mul_f32 v[8:9], v[8:9], v[14:15]
	s_nop 0
	v_cvt_pk_bf16_f32 v14, v8, v9
	v_lshlrev_b32_e32 v8, 16, v27
	v_and_b32_e32 v9, 0xffff0000, v27
	v_mul_f32_e32 v8, 0xbfb8aa3b, v8
	v_mul_f32_e32 v9, 0xbfb8aa3b, v9
	v_exp_f32_e32 v8, v8
	v_exp_f32_e32 v9, v9
	v_add_f32_e32 v8, 1.0, v8
	v_add_f32_e32 v9, 1.0, v9
	v_rcp_f32_e32 v8, v8
	v_rcp_f32_e32 v9, v9
	s_nop 0
	v_pk_mul_f32 v[8:9], v[10:11], v[8:9]
	s_nop 0
	v_cvt_pk_bf16_f32 v15, v8, v9
	global_store_dwordx4 v[38:39], v[12:15], off offset:128
	global_load_dwordx4 v[8:11], v[72:73], off offset:400
	s_nop 0
	global_load_dwordx4 v[12:15], v[72:73], off offset:384
	global_load_dwordx4 v[16:19], v[40:41], off offset:192
	s_waitcnt vmcnt(2)
	v_pk_mul_f32 v[0:1], v[0:1], v[8:9]
	s_waitcnt vmcnt(1)
	v_pk_mul_f32 v[4:5], v[4:5], v[12:13]
	s_waitcnt vmcnt(0)
	v_lshlrev_b32_e32 v20, 16, v16
	v_and_b32_e32 v16, 0xffff0000, v16
	v_mul_f32_e32 v20, 0xbfb8aa3b, v20
	v_mul_f32_e32 v16, 0xbfb8aa3b, v16
	v_exp_f32_e32 v20, v20
	v_exp_f32_e32 v16, v16
	v_pk_mul_f32 v[6:7], v[6:7], v[14:15]
	v_pk_mul_f32 v[2:3], v[2:3], v[10:11]
	v_add_f32_e32 v20, 1.0, v20
	v_add_f32_e32 v16, 1.0, v16
	v_rcp_f32_e32 v20, v20
	v_rcp_f32_e32 v21, v16
	s_nop 0
	v_pk_mul_f32 v[4:5], v[4:5], v[20:21]
	s_nop 0
	v_cvt_pk_bf16_f32 v4, v4, v5
	v_lshlrev_b32_e32 v5, 16, v17
	v_mul_f32_e32 v5, 0xbfb8aa3b, v5
	v_exp_f32_e32 v5, v5
	s_nop 0
	v_add_f32_e32 v5, 1.0, v5
	v_rcp_f32_e32 v12, v5
	v_and_b32_e32 v5, 0xffff0000, v17
	v_mul_f32_e32 v5, 0xbfb8aa3b, v5
	v_exp_f32_e32 v5, v5
	s_nop 0
	v_add_f32_e32 v5, 1.0, v5
	v_rcp_f32_e32 v13, v5
	s_nop 0
	v_pk_mul_f32 v[6:7], v[6:7], v[12:13]
	s_nop 0
	v_cvt_pk_bf16_f32 v5, v6, v7
	v_lshlrev_b32_e32 v6, 16, v18
	v_and_b32_e32 v7, 0xffff0000, v18
	v_mul_f32_e32 v6, 0xbfb8aa3b, v6
	v_mul_f32_e32 v7, 0xbfb8aa3b, v7
	v_exp_f32_e32 v6, v6
	v_exp_f32_e32 v7, v7
	v_add_f32_e32 v6, 1.0, v6
	v_add_f32_e32 v7, 1.0, v7
	v_rcp_f32_e32 v6, v6
	v_rcp_f32_e32 v7, v7
	s_nop 0
	v_pk_mul_f32 v[0:1], v[0:1], v[6:7]
	s_nop 0
	v_cvt_pk_bf16_f32 v6, v0, v1
	v_lshlrev_b32_e32 v0, 16, v19
	v_and_b32_e32 v1, 0xffff0000, v19
	v_mul_f32_e32 v0, 0xbfb8aa3b, v0
	v_mul_f32_e32 v1, 0xbfb8aa3b, v1
	v_exp_f32_e32 v0, v0
	v_exp_f32_e32 v1, v1
	v_add_f32_e32 v0, 1.0, v0
	v_add_f32_e32 v1, 1.0, v1
	v_rcp_f32_e32 v0, v0
	v_rcp_f32_e32 v1, v1
	s_nop 0
	v_pk_mul_f32 v[0:1], v[2:3], v[0:1]
	s_nop 0
	v_cvt_pk_bf16_f32 v7, v0, v1
	global_store_dwordx4 v[38:39], v[4:7], off offset:192
	s_load_dword s0, s[18:19], 0xc8
	s_waitcnt lgkmcnt(0)
	s_add_i32 s33, s33, s0
	s_cmpk_gt_i32 s33, 0x317
	s_cbranch_scc1 .LBB0_748
